# attention loop v6: single score register set, 8-deep K fragment prefetch, grouped lgkmcnt waits, P packed without permlane swaps (V image in MFMA key order), mid-QK barrier after q6
# speedup vs baseline: 1.0182x; 1.0111x over previous
; __device__ __forceinline__ float bflo(unsigned w) { return __uint_as_float(w << 16); }
; __device__ __forceinline__ float bfhi(unsigned w) { return __uint_as_float(w & 0xffff0000u); }
; #define QROPE(RW, GA, GB, E2, OUT) do { int pp = (8 * d0 + 4 * hi + (E2)) & 31; asm volatile("" : "+v"(pp)); const float freq = __builtin_amdgcn_exp2f(-(float)pp * (13.287712379549449f / 32.f)); \
;         float sn, cs; sincos_rev(idx * freq * INV2PI, sn, cs); const float y0 = bflo(RW) * rsc * (GA), y1 = bfhi(RW) * rsc * (GB); OUT = cvtpk(y0 * cs - y1 * sn, y0 * sn + y1 * cs); } while (0)
; __device__ __forceinline__ void attn_unit_fast(const bf16* __restrict__ Qb, const bf16* __restrict__ Kh, const bf16* __restrict__ Vh, bf16* __restrict__ Ob, int NT, char* lds, int t0, const float* __restrict__ qg) {
;     ...
;   const bf16* Qw = Qb + (long)(wid * QBLK + r32) * LDQ + hi * 8;
;   {
;     float ssq = 0.f;
; #pragma unroll
;     for (int d0 = 0; d0 < 8; ++d0) { const v4u rw = *reinterpret_cast<const v4u*>(Qw + d0 * 16);
;       ssq += (bflo(rw.x) * bflo(rw.x) + bfhi(rw.x) * bfhi(rw.x)) + (bflo(rw.y) * bflo(rw.y) + bfhi(rw.y) * bfhi(rw.y));
;       ssq += (bflo(rw.z) * bflo(rw.z) + bfhi(rw.z) * bfhi(rw.z)) + (bflo(rw.w) * bflo(rw.w) + bfhi(rw.w) * bfhi(rw.w)); }
;     { auto rr = __builtin_amdgcn_permlane32_swap(__float_as_uint(ssq), __float_as_uint(ssq), false, false); ssq = __uint_as_float(rr[0]) + __uint_as_float(rr[1]); }
;     const float rsc = (SCALE * 1.4426950408889634f) / sqrtf(ssq * (1.f / 128.f) + EPS);
;     const int t = t0 + wid * QBLK + r32; const float frow = (float)(t >> 6), fcol = (float)(t & 63);
; #pragma unroll
;     for (int d0 = 0; d0 < 8; ++d0) { const v4u rw = *reinterpret_cast<const v4u*>(Qw + d0 * 16);
;       const f32x4 g0 = *reinterpret_cast<const f32x4*>(qg + 16 * d0 + 8 * hi), g1 = *reinterpret_cast<const f32x4*>(qg + 16 * d0 + 8 * hi + 4);
;       const float idx = d0 < 4 ? frow : fcol; v4u wv;
;     ...
;       QROPE(rw.x, g0.x, g0.y, 0, wv.x); QROPE(rw.y, g0.z, g0.w, 1, wv.y); QROPE(rw.z, g1.x, g1.y, 2, wv.z); QROPE(rw.w, g1.z, g1.w, 3, wv.w);
.LBB0_451:
	v_mov_b32_e32 v195, v252
	s_lshl_b64 s[0:1], s[20:21], 1
	v_ashrrev_i32_e32 v0, 1, v195
	v_bfe_u32 v193, v195, 5, 1
	v_and_b32_e32 v178, 0xffffffe0, v0
	v_bfi_b32 v2, s3, v0, v195
	v_mov_b64_e32 v[0:1], s[68:69]
	v_mad_i64_i32 v[0:1], s[4:5], v2, s53, v[0:1]
	v_lshlrev_b32_e32 v176, 4, v193
	v_lshlrev_b32_e32 v16, 2, v193
	v_and_b32_e32 v191, 31, v195
	v_lshl_add_u64 v[0:1], v[0:1], 0, v[176:177]
	v_and_b32_e32 v95, 32, v195
	v_mov_b32_e32 v2, v16
	global_load_dwordx4 v[56:59], v[0:1], off
	global_load_dwordx4 v[60:63], v[0:1], off offset:32
	global_load_dwordx4 v[64:67], v[0:1], off offset:64
	global_load_dwordx4 v[68:71], v[0:1], off offset:96
	global_load_dwordx4 v[72:75], v[0:1], off offset:128
	global_load_dwordx4 v[76:79], v[0:1], off offset:160
	global_load_dwordx4 v[80:83], v[0:1], off offset:192
	global_load_dwordx4 v[84:87], v[0:1], off offset:224
	v_or_b32_e32 v0, s85, v191
	global_load_dwordx4 v[32:35], v95, s[22:23] offset:16
	global_load_dwordx4 v[48:51], v95, s[22:23]
	v_add_u32_e32 v0, v0, v178
	v_cvt_f32_i32_e32 v2, v2
	v_ashrrev_i32_e32 v1, 6, v0
	v_or_b32_e32 v17, 1, v16
	v_cvt_f32_i32_e32 v8, v1
	v_mov_b32_e32 v1, v17
	v_and_b32_e32 v0, 63, v0
	v_cvt_f32_ubyte0_e32 v93, v0
	v_mul_f32_e32 v0, 0xbed49a78, v2
	v_cvt_f32_i32_e32 v1, v1
	v_exp_f32_e32 v0, v0
	v_or_b32_e32 v18, 2, v16
	v_or_b32_e32 v19, 3, v16
	v_mul_f32_e32 v1, 0xbed49a78, v1
	v_mul_f32_e32 v0, v0, v8
	v_exp_f32_e32 v1, v1
	v_mul_f32_e32 v2, 0.15915494, v0
	v_floor_f32_e32 v2, v2
	v_fma_f32 v0, v0, 0.15915494, -v2
	v_mov_b32_e32 v2, v18
	v_sin_f32_e32 v164, v0
	v_cos_f32_e32 v160, v0
	v_mul_f32_e32 v0, v1, v8
	v_mul_f32_e32 v1, 0.15915494, v0
	v_cvt_f32_i32_e32 v2, v2
	v_floor_f32_e32 v1, v1
	v_fma_f32 v0, v0, 0.15915494, -v1
	v_mov_b32_e32 v1, v19
	v_sin_f32_e32 v156, v0
	v_cos_f32_e32 v112, v0
	v_mul_f32_e32 v0, 0xbed49a78, v2
	v_cvt_f32_i32_e32 v1, v1
	v_exp_f32_e32 v0, v0
	v_or_b32_e32 v24, 8, v16
	global_load_dwordx4 v[36:39], v95, s[22:23] offset:80
	global_load_dwordx4 v[40:43], v95, s[22:23] offset:64
	v_mul_f32_e32 v1, 0xbed49a78, v1
	v_mul_f32_e32 v0, v0, v8
	v_exp_f32_e32 v1, v1
	v_mul_f32_e32 v2, 0.15915494, v0
	v_floor_f32_e32 v2, v2
	v_fma_f32 v0, v0, 0.15915494, -v2
	v_mov_b32_e32 v2, v24
	v_sin_f32_e32 v126, v0
	v_cos_f32_e32 v114, v0
	v_mul_f32_e32 v0, v1, v8
	v_mul_f32_e32 v1, 0.15915494, v0
	v_cvt_f32_i32_e32 v2, v2
	v_floor_f32_e32 v1, v1
	v_or_b32_e32 v25, 9, v16
	v_fma_f32 v0, v0, 0.15915494, -v1
	v_mov_b32_e32 v1, v25
	v_sin_f32_e32 v118, v0
	v_cos_f32_e32 v116, v0
	v_mul_f32_e32 v0, 0xbed49a78, v2
	v_cvt_f32_i32_e32 v1, v1
	v_exp_f32_e32 v0, v0
	v_or_b32_e32 v26, 10, v16
	v_or_b32_e32 v27, 11, v16
	v_mul_f32_e32 v1, 0xbed49a78, v1
	v_mul_f32_e32 v0, v0, v8
	v_exp_f32_e32 v1, v1
	v_mul_f32_e32 v2, 0.15915494, v0
	v_floor_f32_e32 v2, v2
	v_fma_f32 v0, v0, 0.15915494, -v2
	v_mov_b32_e32 v2, v26
	v_sin_f32_e32 v122, v0
	v_cos_f32_e32 v120, v0
	v_mul_f32_e32 v0, v1, v8
	v_mul_f32_e32 v1, 0.15915494, v0
	v_cvt_f32_i32_e32 v2, v2
	v_floor_f32_e32 v1, v1
	v_fma_f32 v0, v0, 0.15915494, -v1
	v_mov_b32_e32 v1, v27
	v_sin_f32_e32 v128, v0
	v_cos_f32_e32 v124, v0
	v_mul_f32_e32 v0, 0xbed49a78, v2
	v_cvt_f32_i32_e32 v1, v1
	v_exp_f32_e32 v0, v0
	v_or_b32_e32 v88, 16, v16
	global_load_dwordx4 v[44:47], v95, s[22:23] offset:144
	global_load_dwordx4 v[52:55], v95, s[22:23] offset:128
	v_mul_f32_e32 v1, 0xbed49a78, v1
	v_mul_f32_e32 v0, v0, v8
	v_exp_f32_e32 v1, v1
	v_mul_f32_e32 v2, 0.15915494, v0
	v_floor_f32_e32 v2, v2
	v_fma_f32 v0, v0, 0.15915494, -v2
	v_mov_b32_e32 v2, v88
	v_sin_f32_e32 v162, v0
	v_cos_f32_e32 v158, v0
	v_mul_f32_e32 v0, v1, v8
	v_mul_f32_e32 v1, 0.15915494, v0
	v_cvt_f32_i32_e32 v2, v2
	v_floor_f32_e32 v1, v1
	v_or_b32_e32 v111, 17, v16
	v_fma_f32 v0, v0, 0.15915494, -v1
	v_mov_b32_e32 v1, v111
	v_sin_f32_e32 v168, v0
	v_cos_f32_e32 v166, v0
	v_mul_f32_e32 v0, 0xbed49a78, v2
	v_cvt_f32_i32_e32 v1, v1
	v_exp_f32_e32 v0, v0
	v_or_b32_e32 v109, 18, v16
	v_or_b32_e32 v107, 19, v16
	v_mul_f32_e32 v1, 0xbed49a78, v1
	v_mul_f32_e32 v0, v0, v8
	v_exp_f32_e32 v1, v1
	v_mul_f32_e32 v2, 0.15915494, v0
	v_floor_f32_e32 v2, v2
	v_fma_f32 v0, v0, 0.15915494, -v2
	v_sin_f32_e32 v172, v0
	v_cos_f32_e32 v170, v0
	v_mul_f32_e32 v0, v1, v8
	v_mov_b32_e32 v2, v109
	v_mul_f32_e32 v1, 0.15915494, v0
	v_floor_f32_e32 v1, v1
	v_cvt_f32_i32_e32 v2, v2
	v_fma_f32 v0, v0, 0.15915494, -v1
	v_mov_b32_e32 v1, v107
	v_sin_f32_e32 v180, v0
	v_cvt_f32_i32_e32 v1, v1
	v_cos_f32_e32 v174, v0
	v_mul_f32_e32 v0, 0xbed49a78, v2
	v_exp_f32_e32 v0, v0
	v_mul_f32_e32 v1, 0xbed49a78, v1
	v_exp_f32_e32 v1, v1
	v_or_b32_e32 v99, 24, v16
	v_mul_f32_e32 v0, v0, v8
	v_mul_f32_e32 v2, 0.15915494, v0
	v_floor_f32_e32 v2, v2
	v_fma_f32 v0, v0, 0.15915494, -v2
	v_mul_f32_e32 v9, v1, v8
	v_sin_f32_e32 v186, v0
	v_cos_f32_e32 v184, v0
	v_mul_f32_e32 v0, 0.15915494, v9
	v_mov_b32_e32 v11, v99
	v_floor_f32_e32 v10, v0
	global_load_dwordx4 v[0:3], v95, s[22:23] offset:208
	global_load_dwordx4 v[4:7], v95, s[22:23] offset:192
	v_or_b32_e32 v97, 25, v16
	v_cvt_f32_i32_e32 v11, v11
	v_fma_f32 v9, v9, 0.15915494, -v10
	v_mov_b32_e32 v10, v97
	v_sin_f32_e32 v190, v9
	v_cos_f32_e32 v188, v9
	v_mul_f32_e32 v9, 0xbed49a78, v11
	v_cvt_f32_i32_e32 v10, v10
	v_exp_f32_e32 v9, v9
	v_or_b32_e32 v103, 26, v16
	v_or_b32_e32 v105, 27, v16
	v_mul_f32_e32 v10, 0xbed49a78, v10
	v_mul_f32_e32 v9, v9, v8
	v_exp_f32_e32 v10, v10
	v_mul_f32_e32 v11, 0.15915494, v9
	v_floor_f32_e32 v11, v11
	v_fma_f32 v9, v9, 0.15915494, -v11
	v_mov_b32_e32 v11, v103
	v_sin_f32_e32 v194, v9
	v_cos_f32_e32 v192, v9
	v_mul_f32_e32 v9, v10, v8
	v_mul_f32_e32 v10, 0.15915494, v9
	v_cvt_f32_i32_e32 v11, v11
	v_floor_f32_e32 v10, v10
	v_fma_f32 v9, v9, 0.15915494, -v10
	v_mov_b32_e32 v10, v105
	v_sin_f32_e32 v94, v9
	v_cos_f32_e32 v92, v9
	v_mul_f32_e32 v9, 0xbed49a78, v11
	v_cvt_f32_i32_e32 v10, v10
	v_exp_f32_e32 v9, v9
	s_waitcnt vmcnt(0)
; __device__ __forceinline__ float bflo(unsigned w) { return __uint_as_float(w << 16); }
; __device__ __forceinline__ float bfhi(unsigned w) { return __uint_as_float(w & 0xffff0000u); }
; __device__ __forceinline__ void attn_unit_fast(const bf16* __restrict__ Qb, const bf16* __restrict__ Kh, const bf16* __restrict__ Vh, bf16* __restrict__ Ob, int NT, char* lds, int t0, const float* __restrict__ qg) {
;     ...
;     for (int d0 = 0; d0 < 8; ++d0) { const v4u rw = *reinterpret_cast<const v4u*>(Qw + d0 * 16);
;       ssq += (bflo(rw.x) * bflo(rw.x) + bfhi(rw.x) * bfhi(rw.x)) + (bflo(rw.y) * bflo(rw.y) + bfhi(rw.y) * bfhi(rw.y));
;       ssq += (bflo(rw.z) * bflo(rw.z) + bfhi(rw.z) * bfhi(rw.z)) + (bflo(rw.w) * bflo(rw.w) + bfhi(rw.w) * bfhi(rw.w)); }
;     { auto rr = __builtin_amdgcn_permlane32_swap(__float_as_uint(ssq), __float_as_uint(ssq), false, false); ssq = __uint_as_float(rr[0]) + __uint_as_float(rr[1]); }
;     const float rsc = (SCALE * 1.4426950408889634f) / sqrtf(ssq * (1.f / 128.f) + EPS);
;     const int t = t0 + wid * QBLK + r32; const float frow = (float)(t >> 6), fcol = (float)(t & 63);
; #pragma unroll
;     for (int d0 = 0; d0 < 8; ++d0) { const v4u rw = *reinterpret_cast<const v4u*>(Qw + d0 * 16);
;       const f32x4 g0 = *reinterpret_cast<const f32x4*>(qg + 16 * d0 + 8 * hi), g1 = *reinterpret_cast<const f32x4*>(qg + 16 * d0 + 8 * hi + 4);
;       const float idx = d0 < 4 ? frow : fcol; v4u wv;
	v_and_b32_e32 v89, 0xffff0000, v87
	v_lshlrev_b32_e32 v90, 16, v86
	v_mul_f32_e32 v10, 0xbed49a78, v10
	v_mul_f32_e32 v9, v9, v8
	v_exp_f32_e32 v10, v10
	v_mul_f32_e32 v11, 0.15915494, v9
	v_floor_f32_e32 v11, v11
	v_fma_f32 v9, v9, 0.15915494, -v11
	v_sin_f32_e32 v98, v9
	v_cos_f32_e32 v96, v9
	v_mul_f32_e32 v20, v10, v8
	global_load_dwordx4 v[8:11], v95, s[22:23] offset:272
	global_load_dwordx4 v[12:15], v95, s[22:23] offset:256
	v_mul_f32_e32 v21, 0.15915494, v20
	v_cvt_f32_i32_e32 v16, v16
	v_cvt_f32_i32_e32 v17, v17
	v_floor_f32_e32 v21, v21
	v_fma_f32 v20, v20, 0.15915494, -v21
	v_mul_f32_e32 v16, 0xbed49a78, v16
	v_exp_f32_e32 v16, v16
	v_mul_f32_e32 v17, 0xbed49a78, v17
	v_exp_f32_e32 v17, v17
	v_sin_f32_e32 v102, v20
	v_mul_f32_e32 v16, v16, v93
	v_cos_f32_e32 v104, v20
	v_mul_f32_e32 v20, 0.15915494, v16
	v_floor_f32_e32 v20, v20
	v_fma_f32 v16, v16, 0.15915494, -v20
	v_sin_f32_e32 v108, v16
	v_cos_f32_e32 v106, v16
	v_mul_f32_e32 v16, v17, v93
	v_mul_f32_e32 v17, 0.15915494, v16
	v_cvt_f32_i32_e32 v18, v18
	v_floor_f32_e32 v17, v17
	v_fma_f32 v16, v16, 0.15915494, -v17
	v_sin_f32_e32 v130, v16
	v_cos_f32_e32 v132, v16
	v_mul_f32_e32 v17, 0xbed49a78, v18
	v_cvt_f32_i32_e32 v16, v19
	v_exp_f32_e32 v17, v17
	global_load_dwordx4 v[20:23], v95, s[22:23] offset:336
	global_load_dwordx4 v[28:31], v95, s[22:23] offset:320
	v_mul_f32_e32 v16, 0xbed49a78, v16
	v_exp_f32_e32 v16, v16
	v_mul_f32_e32 v17, v17, v93
	v_mul_f32_e32 v18, 0.15915494, v17
	v_floor_f32_e32 v18, v18
	v_fma_f32 v17, v17, 0.15915494, -v18
	v_mul_f32_e32 v16, v16, v93
	v_sin_f32_e32 v142, v17
	v_cos_f32_e32 v138, v17
	v_mul_f32_e32 v17, 0.15915494, v16
	v_cvt_f32_i32_e32 v18, v24
	v_floor_f32_e32 v17, v17
	v_fma_f32 v16, v16, 0.15915494, -v17
	v_sin_f32_e32 v144, v16
	v_cos_f32_e32 v146, v16
	v_mul_f32_e32 v17, 0xbed49a78, v18
	v_cvt_f32_i32_e32 v16, v25
	v_exp_f32_e32 v17, v17
	v_mul_f32_e32 v16, 0xbed49a78, v16
	v_exp_f32_e32 v16, v16
	v_mul_f32_e32 v17, v17, v93
	v_mul_f32_e32 v18, 0.15915494, v17
	v_floor_f32_e32 v18, v18
	v_fma_f32 v17, v17, 0.15915494, -v18
	v_mul_f32_e32 v16, v16, v93
	v_sin_f32_e32 v150, v17
	v_cos_f32_e32 v148, v17
	v_mul_f32_e32 v17, 0.15915494, v16
	v_cvt_f32_i32_e32 v18, v26
	v_floor_f32_e32 v17, v17
	v_fma_f32 v16, v16, 0.15915494, -v17
	v_sin_f32_e32 v110, v16
	v_cos_f32_e32 v134, v16
	v_cvt_f32_i32_e32 v16, v27
	v_mul_f32_e32 v17, 0xbed49a78, v18
	v_exp_f32_e32 v17, v17
	v_and_b32_e32 v91, 0xffff0000, v86
	v_mul_f32_e32 v16, 0xbed49a78, v16
	v_exp_f32_e32 v16, v16
	v_mul_f32_e32 v17, v17, v93
	v_mul_f32_e32 v18, 0.15915494, v17
	v_floor_f32_e32 v18, v18
	v_fma_f32 v17, v17, 0.15915494, -v18
	v_mul_f32_e32 v16, v16, v93
	v_sin_f32_e32 v140, v17
	v_cos_f32_e32 v136, v17
	v_mul_f32_e32 v17, 0.15915494, v16
	v_floor_f32_e32 v17, v17
	v_fma_f32 v113, v16, 0.15915494, -v17
	global_load_dwordx4 v[16:19], v95, s[22:23] offset:400
	global_load_dwordx4 v[24:27], v95, s[22:23] offset:384
	v_lshlrev_b32_e32 v86, 16, v85
	v_cvt_f32_i32_e32 v115, v88
	v_lshlrev_b32_e32 v88, 16, v87
	v_and_b32_e32 v87, 0xffff0000, v85
	v_and_b32_e32 v85, 0xffff0000, v83
	v_and_b32_e32 v153, 0xffff0000, v82
	v_lshlrev_b32_e32 v100, 16, v84
	v_and_b32_e32 v101, 0xffff0000, v84
	v_lshlrev_b32_e32 v84, 16, v83
	v_lshlrev_b32_e32 v152, 16, v82
	v_mov_b32_e32 v154, v153
	v_mov_b32_e32 v155, v85
	v_mov_b32_e32 v82, v152
	v_mov_b32_e32 v83, v84
	v_pk_mul_f32 v[154:155], v[154:155], v[154:155]
	v_and_b32_e32 v197, 0xffff0000, v76
	v_pk_fma_f32 v[212:213], v[82:83], v[82:83], v[154:155]
	v_lshlrev_b32_e32 v82, 16, v81
	v_and_b32_e32 v83, 0xffff0000, v81
	v_lshlrev_b32_e32 v154, 16, v80
	v_and_b32_e32 v155, 0xffff0000, v80
	v_lshlrev_b32_e32 v80, 16, v79
	v_and_b32_e32 v81, 0xffff0000, v79
	v_and_b32_e32 v79, 0xffff0000, v77
	v_lshlrev_b32_e32 v182, 16, v78
	v_and_b32_e32 v183, 0xffff0000, v78
	v_lshlrev_b32_e32 v78, 16, v77
	v_lshlrev_b32_e32 v196, 16, v76
	v_mov_b32_e32 v198, v197
	v_mov_b32_e32 v199, v79
	v_mov_b32_e32 v76, v196
	v_mov_b32_e32 v77, v78
	v_pk_mul_f32 v[198:199], v[198:199], v[198:199]
	v_and_b32_e32 v203, 0xffff0000, v70
	v_pk_fma_f32 v[214:215], v[76:77], v[76:77], v[198:199]
	v_lshlrev_b32_e32 v76, 16, v75
	v_and_b32_e32 v77, 0xffff0000, v75
	v_lshlrev_b32_e32 v198, 16, v74
	v_and_b32_e32 v199, 0xffff0000, v74
	v_lshlrev_b32_e32 v74, 16, v73
	v_and_b32_e32 v75, 0xffff0000, v73
	v_and_b32_e32 v73, 0xffff0000, v71
	v_lshlrev_b32_e32 v200, 16, v72
	v_and_b32_e32 v201, 0xffff0000, v72
	v_lshlrev_b32_e32 v72, 16, v71
	v_lshlrev_b32_e32 v202, 16, v70
	v_mov_b32_e32 v204, v203
	v_mov_b32_e32 v205, v73
	v_and_b32_e32 v245, 0xffff0000, v59
	v_and_b32_e32 v219, 0xffff0000, v58
	v_mov_b32_e32 v70, v202
	v_mov_b32_e32 v71, v72
	v_pk_mul_f32 v[204:205], v[204:205], v[204:205]
	v_lshlrev_b32_e32 v240, 16, v61
	v_and_b32_e32 v241, 0xffff0000, v61
	v_lshlrev_b32_e32 v242, 16, v60
	v_and_b32_e32 v243, 0xffff0000, v60
	v_lshlrev_b32_e32 v244, 16, v59
	v_lshlrev_b32_e32 v218, 16, v58
	v_mov_b32_e32 v60, v219
	v_mov_b32_e32 v61, v245
	v_pk_fma_f32 v[210:211], v[70:71], v[70:71], v[204:205]
	v_lshlrev_b32_e32 v70, 16, v69
	v_and_b32_e32 v71, 0xffff0000, v69
	v_lshlrev_b32_e32 v232, 16, v68
	v_and_b32_e32 v233, 0xffff0000, v68
	v_lshlrev_b32_e32 v68, 16, v67
	v_and_b32_e32 v69, 0xffff0000, v67
	v_and_b32_e32 v67, 0xffff0000, v65
	v_and_b32_e32 v237, 0xffff0000, v64
	v_mov_b32_e32 v58, v218
	v_mov_b32_e32 v59, v244
	v_pk_mul_f32 v[60:61], v[60:61], v[60:61]
	v_and_b32_e32 v221, 0xffff0000, v57
	v_and_b32_e32 v223, 0xffff0000, v56
	v_lshlrev_b32_e32 v234, 16, v66
	v_and_b32_e32 v235, 0xffff0000, v66
	v_lshlrev_b32_e32 v66, 16, v65
	v_lshlrev_b32_e32 v236, 16, v64
; __device__ __forceinline__ float bflo(unsigned w) { return __uint_as_float(w << 16); }
; __device__ __forceinline__ float bfhi(unsigned w) { return __uint_as_float(w & 0xffff0000u); }
; __device__ __forceinline__ void attn_unit_fast(const bf16* __restrict__ Qb, const bf16* __restrict__ Kh, const bf16* __restrict__ Vh, bf16* __restrict__ Ob, int NT, char* lds, int t0, const float* __restrict__ qg) {
;     ...
;     float ssq = 0.f;
; #pragma unroll
;     for (int d0 = 0; d0 < 8; ++d0) { const v4u rw = *reinterpret_cast<const v4u*>(Qw + d0 * 16);
;       ssq += (bflo(rw.x) * bflo(rw.x) + bfhi(rw.x) * bfhi(rw.x)) + (bflo(rw.y) * bflo(rw.y) + bfhi(rw.y) * bfhi(rw.y));
;       ssq += (bflo(rw.z) * bflo(rw.z) + bfhi(rw.z) * bfhi(rw.z)) + (bflo(rw.w) * bflo(rw.w) + bfhi(rw.w) * bfhi(rw.w)); }
;     { auto rr = __builtin_amdgcn_permlane32_swap(__float_as_uint(ssq), __float_as_uint(ssq), false, false); ssq = __uint_as_float(rr[0]) + __uint_as_float(rr[1]); }
;     const float rsc = (SCALE * 1.4426950408889634f) / sqrtf(ssq * (1.f / 128.f) + EPS);
;     const int t = t0 + wid * QBLK + r32; const float frow = (float)(t >> 6), fcol = (float)(t & 63);
; #pragma unroll
;     for (int d0 = 0; d0 < 8; ++d0) { const v4u rw = *reinterpret_cast<const v4u*>(Qw + d0 * 16);
;       const f32x4 g0 = *reinterpret_cast<const f32x4*>(qg + 16 * d0 + 8 * hi), g1 = *reinterpret_cast<const f32x4*>(qg + 16 * d0 + 8 * hi + 4);
;       const float idx = d0 < 4 ? frow : fcol; v4u wv;
	v_mov_b32_e32 v204, v237
	v_mov_b32_e32 v205, v67
	v_pk_fma_f32 v[58:59], v[58:59], v[58:59], v[60:61]
	v_lshlrev_b32_e32 v220, 16, v57
	v_lshlrev_b32_e32 v222, 16, v56
	v_mov_b32_e32 v60, v223
	v_mov_b32_e32 v61, v221
	v_mov_b32_e32 v64, v236
	v_mov_b32_e32 v65, v66
	v_pk_mul_f32 v[204:205], v[204:205], v[204:205]
	v_mov_b32_e32 v56, v222
	v_mov_b32_e32 v57, v220
	v_pk_mul_f32 v[60:61], v[60:61], v[60:61]
	v_pk_fma_f32 v[206:207], v[64:65], v[64:65], v[204:205]
	v_lshlrev_b32_e32 v64, 16, v63
	v_and_b32_e32 v65, 0xffff0000, v63
	v_lshlrev_b32_e32 v238, 16, v62
	v_and_b32_e32 v239, 0xffff0000, v62
	v_mul_f32_e32 v62, v240, v240
	v_pk_fma_f32 v[56:57], v[56:57], v[56:57], v[60:61]
	v_mul_f32_e32 v60, v242, v242
	v_pk_mul_f32 v[204:205], v[64:65], v[64:65]
	v_pk_fma_f32 v[62:63], v[240:241], v[240:241], v[62:63] op_sel_hi:[1,1,0]
	v_pk_fma_f32 v[208:209], v[242:243], v[242:243], v[60:61] op_sel_hi:[1,1,0]
	v_mov_b32_e32 v62, v205
	v_mov_b32_e32 v208, v204
	v_pk_mul_f32 v[204:205], v[238:239], v[238:239]
	v_pk_add_f32 v[58:59], v[58:59], v[58:59] op_sel_hi:[0,1]
	v_pk_add_f32 v[56:57], v[56:57], v[56:57] op_sel_hi:[0,1]
	v_mov_b32_e32 v58, v204
	v_mov_b32_e32 v56, v205
	v_pk_add_f32 v[56:57], v[58:59], v[56:57]
	v_mul_f32_e32 v58, v68, v68
	v_pk_fma_f32 v[58:59], v[68:69], v[68:69], v[58:59] op_sel_hi:[1,1,0]
	v_cvt_f32_i32_e32 v111, v111
	v_pk_add_f32 v[62:63], v[208:209], v[62:63]
	v_mul_f32_e32 v58, v234, v234
	v_pk_mul_f32 v[204:205], v[232:233], v[232:233]
	v_pk_add_f32 v[56:57], v[56:57], v[62:63]
	v_pk_fma_f32 v[62:63], v[234:235], v[234:235], v[58:59] op_sel_hi:[1,1,0]
	v_mul_f32_e32 v61, 0xbed49a78, v115
	v_mov_b32_e32 v62, v204
	v_mov_b32_e32 v58, v205
	v_exp_f32_e32 v61, v61
	v_mul_f32_e32 v111, 0xbed49a78, v111
	v_pk_add_f32 v[58:59], v[62:63], v[58:59]
	v_pk_mul_f32 v[62:63], v[70:71], v[70:71]
	v_pk_add_f32 v[206:207], v[206:207], v[206:207] op_sel_hi:[0,1]
	v_pk_add_f32 v[56:57], v[56:57], v[56:57] op_sel_hi:[0,1]
	v_exp_f32_e32 v111, v111
	v_mov_b32_e32 v206, v62
	v_mov_b32_e32 v56, v63
	v_pk_add_f32 v[56:57], v[206:207], v[56:57]
	v_mul_f32_e32 v61, v61, v93
	v_pk_add_f32 v[56:57], v[58:59], v[56:57]
	v_mul_f32_e32 v58, v200, v200
	v_pk_mul_f32 v[62:63], v[198:199], v[198:199]
	v_mul_f32_e32 v206, v74, v74
	v_pk_fma_f32 v[58:59], v[200:201], v[200:201], v[58:59] op_sel_hi:[1,1,0]
	v_sin_f32_e32 v60, v113
	v_cos_f32_e32 v204, v113
	v_mul_f32_e32 v113, 0.15915494, v61
	v_pk_fma_f32 v[216:217], v[74:75], v[74:75], v[206:207] op_sel_hi:[1,1,0]
	v_mov_b32_e32 v58, v62
	v_mul_f32_e32 v62, v111, v93
	v_floor_f32_e32 v113, v113
	v_mov_b32_e32 v216, v63
	v_mul_f32_e32 v63, 0.15915494, v62
	v_fma_f32 v61, v61, 0.15915494, -v113
	v_floor_f32_e32 v63, v63
	v_sin_f32_e32 v208, v61
	v_fma_f32 v111, v62, 0.15915494, -v63
	v_cos_f32_e32 v206, v61
	v_pk_mul_f32 v[62:63], v[76:77], v[76:77]
	v_cvt_f32_i32_e32 v61, v109
	v_pk_add_f32 v[210:211], v[210:211], v[210:211] op_sel_hi:[0,1]
	v_pk_add_f32 v[56:57], v[56:57], v[56:57] op_sel_hi:[0,1]
	v_mov_b32_e32 v210, v62
	v_mov_b32_e32 v56, v63
	v_pk_add_f32 v[58:59], v[58:59], v[216:217]
	v_pk_add_f32 v[56:57], v[210:211], v[56:57]
	v_mul_f32_e32 v210, v80, v80
	v_pk_add_f32 v[56:57], v[58:59], v[56:57]
	v_mul_f32_e32 v58, v182, v182
	v_pk_mul_f32 v[62:63], v[154:155], v[154:155]
	v_pk_fma_f32 v[216:217], v[80:81], v[80:81], v[210:211] op_sel_hi:[1,1,0]
	v_pk_fma_f32 v[58:59], v[182:183], v[182:183], v[58:59] op_sel_hi:[1,1,0]
	v_mul_f32_e32 v61, 0xbed49a78, v61
	v_mov_b32_e32 v58, v62
	v_mov_b32_e32 v216, v63
	v_exp_f32_e32 v61, v61
	v_pk_mul_f32 v[62:63], v[82:83], v[82:83]
	v_pk_add_f32 v[214:215], v[214:215], v[214:215] op_sel_hi:[0,1]
	v_pk_add_f32 v[56:57], v[56:57], v[56:57] op_sel_hi:[0,1]
	v_mov_b32_e32 v214, v62
	v_mov_b32_e32 v56, v63
	v_pk_add_f32 v[58:59], v[58:59], v[216:217]
	v_pk_add_f32 v[56:57], v[214:215], v[56:57]
	v_pk_mul_f32 v[62:63], v[90:91], v[90:91]
	v_pk_add_f32 v[56:57], v[58:59], v[56:57]
	v_mul_f32_e32 v58, v100, v100
	v_mul_f32_e32 v214, v86, v86
	v_pk_fma_f32 v[58:59], v[100:101], v[100:101], v[58:59] op_sel_hi:[1,1,0]
	v_mul_f32_e32 v61, v61, v93
	v_pk_fma_f32 v[214:215], v[86:87], v[86:87], v[214:215] op_sel_hi:[1,1,0]
	v_mov_b32_e32 v58, v62
	v_mul_f32_e32 v62, 0.15915494, v61
	v_mov_b32_e32 v214, v63
	v_floor_f32_e32 v109, v62
	v_pk_mul_f32 v[62:63], v[88:89], v[88:89]
	v_pk_add_f32 v[212:213], v[212:213], v[212:213] op_sel_hi:[0,1]
	v_pk_add_f32 v[56:57], v[56:57], v[56:57] op_sel_hi:[0,1]
	v_mov_b32_e32 v212, v62
	v_mov_b32_e32 v56, v63
	v_pk_add_f32 v[58:59], v[58:59], v[214:215]
	v_pk_add_f32 v[56:57], v[212:213], v[56:57]
	s_add_u32 s44, s16, s0
	v_pk_add_f32 v[56:57], v[58:59], v[56:57]
	v_fma_f32 v58, v61, 0.15915494, -v109
	v_pk_add_f32 v[56:57], v[56:57], v[56:57] op_sel:[0,1] op_sel_hi:[1,0]
	v_cvt_f32_i32_e32 v107, v107
	v_mov_b32_e32 v57, v56
	s_nop 1
	v_permlane32_swap_b32_e32 v56, v57
	v_add_f32_e32 v56, v56, v57
	v_fmamk_f32 v56, v56, 0x3c000000, v185
	v_mul_f32_e32 v57, 0x4f800000, v56
	v_cmp_gt_f32_e32 vcc, s89, v56
	v_mul_f32_e32 v59, 0xbed49a78, v107
	v_exp_f32_e32 v59, v59
	v_cndmask_b32_e32 v56, v56, v57, vcc
	v_sqrt_f32_e32 v57, v56
	v_sin_f32_e32 v230, v58
	v_cos_f32_e32 v228, v58
	v_mul_f32_e32 v63, v59, v93
	v_add_u32_e32 v61, -1, v57
	v_fma_f32 v62, -v61, v57, v56
	v_cmp_ge_f32_e64 s[4:5], 0, v62
	v_add_u32_e32 v62, 1, v57
	s_addc_u32 s45, s17, s1
	v_cndmask_b32_e64 v61, v57, v61, s[4:5]
	v_fma_f32 v57, -v62, v57, v56
	v_cmp_lt_f32_e64 s[4:5], 0, v57
	s_add_u32 s66, s18, s0
	s_addc_u32 s67, s19, s1
	v_cndmask_b32_e64 v57, v61, v62, s[4:5]
	v_mul_f32_e32 v61, 0x37800000, v57
	v_cndmask_b32_e32 v57, v57, v61, vcc
	v_cmp_class_f32_e32 vcc, v56, v187
; #define QROPE(RW, GA, GB, E2, OUT) do { int pp = (8 * d0 + 4 * hi + (E2)) & 31; asm volatile("" : "+v"(pp)); const float freq = __builtin_amdgcn_exp2f(-(float)pp * (13.287712379549449f / 32.f)); \
;         float sn, cs; sincos_rev(idx * freq * INV2PI, sn, cs); const float y0 = bflo(RW) * rsc * (GA), y1 = bfhi(RW) * rsc * (GB); OUT = cvtpk(y0 * cs - y1 * sn, y0 * sn + y1 * cs); } while (0)
; __device__ __forceinline__ void attn_unit_fast(const bf16* __restrict__ Qb, const bf16* __restrict__ Kh, const bf16* __restrict__ Vh, bf16* __restrict__ Ob, int NT, char* lds, int t0, const float* __restrict__ qg) {
;     ...
;     const float rsc = (SCALE * 1.4426950408889634f) / sqrtf(ssq * (1.f / 128.f) + EPS);
;     const int t = t0 + wid * QBLK + r32; const float frow = (float)(t >> 6), fcol = (float)(t & 63);
; #pragma unroll
;     for (int d0 = 0; d0 < 8; ++d0) { const v4u rw = *reinterpret_cast<const v4u*>(Qw + d0 * 16);
;       const f32x4 g0 = *reinterpret_cast<const f32x4*>(qg + 16 * d0 + 8 * hi), g1 = *reinterpret_cast<const f32x4*>(qg + 16 * d0 + 8 * hi + 4);
;       const float idx = d0 < 4 ? frow : fcol; v4u wv;
;     ...
;       QROPE(rw.x, g0.x, g0.y, 0, wv.x); QROPE(rw.y, g0.z, g0.w, 1, wv.y); QROPE(rw.z, g1.x, g1.y, 2, wv.z); QROPE(rw.w, g1.z, g1.w, 3, wv.w);
;     ...
;       qr[d0] = __builtin_bit_cast(bf16x8, wv); }
	v_sin_f32_e32 v210, v111
	v_cos_f32_e32 v216, v111
	v_cndmask_b32_e32 v56, v57, v56, vcc
	v_div_scale_f32 v57, s[4:5], v56, v56, s72
	v_rcp_f32_e32 v61, v57
	v_and_b32_e32 v179, 63, v195
	s_cmp_lg_u32 0, -1
	s_cselect_b32 s4, 0, 0
	v_fma_f32 v58, -v57, v61, 1.0
	v_fmac_f32_e32 v61, v58, v61
	v_div_scale_f32 v58, vcc, s72, v56, s72
	v_mul_f32_e32 v59, v58, v61
	v_fma_f32 v62, -v57, v59, v58
	v_fmac_f32_e32 v59, v62, v61
	v_fma_f32 v57, -v57, v59, v58
	v_div_fmas_f32 v57, v57, v61, v59
	v_div_fixup_f32 v62, v57, v56, s72
	v_pk_mul_f32 v[56:57], v[62:63], v[222:223] op_sel_hi:[0,1]
	v_pk_mul_f32 v[48:49], v[48:49], v[56:57]
	s_mov_b32 s20, 4
	v_pk_mul_f32 v[56:57], v[48:49], v[164:165] op_sel:[1,0] op_sel_hi:[0,0]
	v_pk_fma_f32 v[222:223], v[48:49], v[160:161], v[56:57] neg_lo:[0,0,1] neg_hi:[0,0,1]
	v_pk_fma_f32 v[160:161], v[48:49], v[160:161], v[56:57] op_sel_hi:[1,0,1]
	v_pk_mul_f32 v[48:49], v[62:63], v[220:221] op_sel_hi:[0,1]
	v_pk_mul_f32 v[164:165], v[50:51], v[48:49]
	global_load_dwordx4 v[48:51], v95, s[22:23] offset:464
	global_load_dwordx4 v[56:59], v95, s[22:23] offset:448
	v_mul_f32_e32 v95, 0.15915494, v63
	v_cvt_f32_i32_e32 v61, v99
	v_floor_f32_e32 v95, v95
	v_fma_f32 v63, v63, 0.15915494, -v95
	v_mul_f32_e32 v61, 0xbed49a78, v61
	v_exp_f32_e32 v61, v61
	v_cvt_f32_i32_e32 v95, v97
	v_pk_mul_f32 v[156:157], v[164:165], v[156:157] op_sel:[1,0] op_sel_hi:[0,0]
	v_pk_fma_f32 v[220:221], v[164:165], v[112:113], v[156:157] neg_lo:[0,0,1] neg_hi:[0,0,1]
	v_mul_f32_e32 v61, v61, v93
	v_pk_fma_f32 v[112:113], v[164:165], v[112:113], v[156:157] op_sel_hi:[1,0,1]
	v_sin_f32_e32 v212, v63
	v_cos_f32_e32 v164, v63
	v_mul_f32_e32 v63, 0.15915494, v61
	v_floor_f32_e32 v63, v63
	v_fma_f32 v61, v61, 0.15915494, -v63
	v_mul_f32_e32 v63, 0xbed49a78, v95
	v_exp_f32_e32 v63, v63
	v_sin_f32_e32 v214, v61
	v_cos_f32_e32 v160, v61
	v_mul_f32_e32 v61, v63, v93
	v_mul_f32_e32 v63, 0.15915494, v61
	v_floor_f32_e32 v63, v63
	v_fma_f32 v61, v61, 0.15915494, -v63
	v_cvt_f32_i32_e32 v63, v103
	v_cvt_pk_bf16_f32 v112, v222, v161
	v_sin_f32_e32 v222, v61
	v_pk_mul_f32 v[156:157], v[62:63], v[218:219] op_sel_hi:[0,1]
	v_pk_mul_f32 v[32:33], v[32:33], v[156:157]
	v_cos_f32_e32 v224, v61
	v_pk_mul_f32 v[126:127], v[32:33], v[126:127] op_sel:[1,0] op_sel_hi:[0,0]
	v_pk_fma_f32 v[156:157], v[32:33], v[114:115], v[126:127] neg_lo:[0,0,1] neg_hi:[0,0,1]
	v_pk_fma_f32 v[32:33], v[32:33], v[114:115], v[126:127] op_sel_hi:[1,0,1]
	v_cvt_pk_bf16_f32 v113, v220, v113
	v_mul_f32_e32 v32, 0xbed49a78, v63
	v_cvt_f32_i32_e32 v63, v105
	v_exp_f32_e32 v32, v32
	v_cvt_pk_bf16_f32 v114, v156, v33
	v_lshlrev_b32_e32 v33, 3, v195
	v_mul_f32_e32 v63, 0xbed49a78, v63
	v_exp_f32_e32 v63, v63
	v_mul_f32_e32 v32, v32, v93
	v_mul_f32_e32 v61, 0.15915494, v32
	v_floor_f32_e32 v61, v61
	v_fma_f32 v32, v32, 0.15915494, -v61
	v_mul_f32_e32 v61, v63, v93
	v_mul_f32_e32 v63, 0.15915494, v61
	v_floor_f32_e32 v63, v63
	v_pk_mul_f32 v[126:127], v[62:63], v[244:245] op_sel_hi:[0,1]
	v_pk_mul_f32 v[34:35], v[34:35], v[126:127]
	v_fma_f32 v61, v61, 0.15915494, -v63
	v_pk_mul_f32 v[118:119], v[34:35], v[118:119] op_sel:[1,0] op_sel_hi:[0,0]
	v_pk_fma_f32 v[126:127], v[34:35], v[116:117], v[118:119] neg_lo:[0,0,1] neg_hi:[0,0,1]
	v_pk_fma_f32 v[34:35], v[34:35], v[116:117], v[118:119] op_sel_hi:[1,0,1]
	v_sin_f32_e32 v220, v32
	v_cvt_pk_bf16_f32 v115, v126, v35
	v_pk_mul_f32 v[34:35], v[62:63], v[242:243] op_sel_hi:[0,1]
	v_pk_mul_f32 v[34:35], v[40:41], v[34:35]
	v_cos_f32_e32 v226, v32
	v_pk_mul_f32 v[40:41], v[34:35], v[122:123] op_sel:[1,0] op_sel_hi:[0,0]
	v_pk_fma_f32 v[116:117], v[34:35], v[120:121], v[40:41] neg_lo:[0,0,1] neg_hi:[0,0,1]
	v_pk_fma_f32 v[34:35], v[34:35], v[120:121], v[40:41] op_sel_hi:[1,0,1]
	v_sin_f32_e32 v218, v61
	v_cvt_pk_bf16_f32 v116, v116, v35
	v_pk_mul_f32 v[34:35], v[62:63], v[240:241] op_sel_hi:[0,1]
	v_pk_mul_f32 v[34:35], v[42:43], v[34:35]
	v_cos_f32_e32 v32, v61
	v_pk_mul_f32 v[40:41], v[34:35], v[128:129] op_sel:[1,0] op_sel_hi:[0,0]
	v_pk_fma_f32 v[42:43], v[34:35], v[124:125], v[40:41] neg_lo:[0,0,1] neg_hi:[0,0,1]
	v_pk_fma_f32 v[34:35], v[34:35], v[124:125], v[40:41] op_sel_hi:[1,0,1]
	s_nop 0
	v_cvt_pk_bf16_f32 v117, v42, v35
	v_pk_mul_f32 v[34:35], v[62:63], v[238:239] op_sel_hi:[0,1]
	v_pk_mul_f32 v[34:35], v[34:35], v[36:37]
	s_nop 0
	v_pk_mul_f32 v[36:37], v[34:35], v[162:163] op_sel:[1,0] op_sel_hi:[0,0]
	v_pk_fma_f32 v[40:41], v[34:35], v[158:159], v[36:37] neg_lo:[0,0,1] neg_hi:[0,0,1]
	v_pk_fma_f32 v[34:35], v[34:35], v[158:159], v[36:37] op_sel_hi:[1,0,1]
	s_nop 0
	v_cvt_pk_bf16_f32 v118, v40, v35
	v_pk_mul_f32 v[34:35], v[62:63], v[64:65] op_sel_hi:[0,1]
	v_pk_mul_f32 v[34:35], v[34:35], v[38:39]
	s_nop 0
	v_pk_mul_f32 v[36:37], v[34:35], v[168:169] op_sel:[1,0] op_sel_hi:[0,0]
	v_pk_fma_f32 v[38:39], v[34:35], v[166:167], v[36:37] neg_lo:[0,0,1] neg_hi:[0,0,1]
	v_pk_fma_f32 v[34:35], v[34:35], v[166:167], v[36:37] op_sel_hi:[1,0,1]
	s_nop 0
	v_cvt_pk_bf16_f32 v119, v38, v35
	v_pk_mul_f32 v[34:35], v[62:63], v[236:237] op_sel_hi:[0,1]
	v_pk_mul_f32 v[34:35], v[34:35], v[52:53]
	s_nop 0
	v_pk_mul_f32 v[36:37], v[34:35], v[172:173] op_sel:[1,0] op_sel_hi:[0,0]
	v_pk_fma_f32 v[38:39], v[34:35], v[170:171], v[36:37] neg_lo:[0,0,1] neg_hi:[0,0,1]
	v_pk_fma_f32 v[34:35], v[34:35], v[170:171], v[36:37] op_sel_hi:[1,0,1]
	s_nop 0
	v_cvt_pk_bf16_f32 v120, v38, v35
	v_pk_mul_f32 v[34:35], v[62:63], v[66:67] op_sel_hi:[0,1]
	v_pk_mul_f32 v[34:35], v[34:35], v[54:55]
	s_nop 0
	v_pk_mul_f32 v[36:37], v[34:35], v[180:181] op_sel:[1,0] op_sel_hi:[0,0]
	v_pk_fma_f32 v[38:39], v[34:35], v[174:175], v[36:37] neg_lo:[0,0,1] neg_hi:[0,0,1]
; __device__ __forceinline__ int v_st(int k, int c) { const int kk = (k & ~0xC) | ((k & 4) << 1) | ((k & 8) >> 1); return ((kk >> 3) * 4 + (c >> 5)) * 512 + ((kk & 7) * 32 + (c & 31)) * 2; }
; __device__ __forceinline__ int v_rd_base(int lane) { return ((lane & 3) << 3) | (((lane >> 2) & 3) << 6) | (((lane >> 4) & 1) << 5) | (((lane >> 5) & 1) << 8); }
; #define QROPE(RW, GA, GB, E2, OUT) do { int pp = (8 * d0 + 4 * hi + (E2)) & 31; asm volatile("" : "+v"(pp)); const float freq = __builtin_amdgcn_exp2f(-(float)pp * (13.287712379549449f / 32.f)); \
;         float sn, cs; sincos_rev(idx * freq * INV2PI, sn, cs); const float y0 = bflo(RW) * rsc * (GA), y1 = bfhi(RW) * rsc * (GB); OUT = cvtpk(y0 * cs - y1 * sn, y0 * sn + y1 * cs); } while (0)
; #define SLOAD(i, k0) do { sr_[i].vs0 = *reinterpret_cast<const bf16x8*>(&Vh[(long)((k0) + sr) * LDK + sc]); sr_[i].vs1 = *reinterpret_cast<const bf16x8*>(&Vh[(long)((k0) + 32 + sr) * LDK + sc]); \
;     sr_[i].ks0 = *reinterpret_cast<const bf16x8*>(&Kh[(long)((k0) + sr) * LDK + sc]); sr_[i].ks1 = *reinterpret_cast<const bf16x8*>(&Kh[(long)((k0) + 32 + sr) * LDK + sc]); } while (0)
; __device__ __forceinline__ void attn_unit_fast(const bf16* __restrict__ Qb, const bf16* __restrict__ Kh, const bf16* __restrict__ Vh, bf16* __restrict__ Ob, int NT, char* lds, int t0, const float* __restrict__ qg) {
;     ...
;     for (int d0 = 0; d0 < 8; ++d0) { const v4u rw = *reinterpret_cast<const v4u*>(Qw + d0 * 16);
;       const f32x4 g0 = *reinterpret_cast<const f32x4*>(qg + 16 * d0 + 8 * hi), g1 = *reinterpret_cast<const f32x4*>(qg + 16 * d0 + 8 * hi + 4);
;       const float idx = d0 < 4 ? frow : fcol; v4u wv;
;     ...
;       QROPE(rw.x, g0.x, g0.y, 0, wv.x); QROPE(rw.y, g0.z, g0.w, 1, wv.y); QROPE(rw.z, g1.x, g1.y, 2, wv.z); QROPE(rw.w, g1.z, g1.w, 3, wv.w);
;     ...
;       qr[d0] = __builtin_bit_cast(bf16x8, wv); }
;     ...
;   const int sr = tid >> 4, sc = (tid & 15) * 8, vst0 = v_st(sr, sc), vst1 = v_st(32 + sr, sc);
;   const int vb0 = (int)(uintptr_t)V_lds + v_rd_base(lane);
;   struct { bf16x8 vs0, vs1, ks0, ks1; } sr_[2];
;     ...
;   f32x16 pA0, pA1, pB0, pB1; bf16x8 pa0, pa1, pa2, pa3;
;   constexpr int SE = 0, SO = 1;
;   SLOAD(SE, 0); asm volatile("s_waitcnt vmcnt(0)" ::: "memory"); SWRITE(0, SE); __syncthreads();
	v_pk_fma_f32 v[34:35], v[34:35], v[174:175], v[36:37] op_sel_hi:[1,0,1]
	s_nop 0
	v_cvt_pk_bf16_f32 v121, v38, v35
	v_pk_mul_f32 v[34:35], v[62:63], v[234:235] op_sel_hi:[0,1]
	v_pk_mul_f32 v[34:35], v[34:35], v[44:45]
	s_nop 0
	v_pk_mul_f32 v[36:37], v[34:35], v[186:187] op_sel:[1,0] op_sel_hi:[0,0]
	v_pk_fma_f32 v[38:39], v[34:35], v[184:185], v[36:37] neg_lo:[0,0,1] neg_hi:[0,0,1]
	v_pk_fma_f32 v[34:35], v[34:35], v[184:185], v[36:37] op_sel_hi:[1,0,1]
	s_nop 0
	v_cvt_pk_bf16_f32 v122, v38, v35
	v_pk_mul_f32 v[34:35], v[62:63], v[68:69] op_sel_hi:[0,1]
	v_pk_mul_f32 v[34:35], v[34:35], v[46:47]
	v_ashrrev_i32_e32 v46, 4, v195
	v_pk_mul_f32 v[36:37], v[34:35], v[190:191] op_sel:[1,0] op_sel_hi:[0,0]
	v_pk_fma_f32 v[38:39], v[34:35], v[188:189], v[36:37] neg_lo:[0,0,1] neg_hi:[0,0,1]
	v_pk_fma_f32 v[34:35], v[34:35], v[188:189], v[36:37] op_sel_hi:[1,0,1]
	v_add_u32_e32 v64, 32, v46
	v_cvt_pk_bf16_f32 v123, v38, v35
	v_pk_mul_f32 v[34:35], v[62:63], v[232:233] op_sel_hi:[0,1]
	v_pk_mul_f32 v[4:5], v[34:35], v[4:5]
	v_ashrrev_i32_e32 v47, 31, v46
	v_pk_mul_f32 v[34:35], v[4:5], v[194:195] op_sel:[1,0] op_sel_hi:[0,0]
	v_pk_fma_f32 v[36:37], v[4:5], v[192:193], v[34:35] neg_lo:[0,0,1] neg_hi:[0,0,1]
	v_pk_fma_f32 v[4:5], v[4:5], v[192:193], v[34:35] op_sel_hi:[1,0,1]
	v_lshlrev_b64 v[34:35], 8, v[46:47]
	v_and_b32_e32 v4, 0x78, v33
	v_lshlrev_b32_e32 v61, 1, v4
	v_ashrrev_i32_e32 v65, 31, v64
	v_cvt_pk_bf16_f32 v124, v36, v5
	v_or_b32_e32 v36, v34, v61
	v_mov_b32_e32 v37, v35
	v_lshlrev_b64 v[52:53], 8, v[64:65]
	v_lshl_add_u64 v[4:5], s[66:67], 0, v[36:37]
	v_or_b32_e32 v52, v52, v61
	global_load_dwordx4 v[38:41], v[4:5], off
	v_lshl_add_u64 v[4:5], s[66:67], 0, v[52:53]
	global_load_dwordx4 v[42:45], v[4:5], off
	v_pk_mul_f32 v[4:5], v[62:63], v[70:71] op_sel_hi:[0,1]
	v_pk_mul_f32 v[54:55], v[4:5], v[6:7]
	v_lshl_add_u64 v[4:5], s[44:45], 0, v[36:37]
	global_load_dwordx4 v[4:7], v[4:5], off
	v_pk_mul_f32 v[66:67], v[54:55], v[94:95] op_sel:[1,0] op_sel_hi:[0,0]
	v_lshl_add_u64 v[52:53], s[44:45], 0, v[52:53]
	v_pk_fma_f32 v[68:69], v[54:55], v[92:93], v[66:67] neg_lo:[0,0,1] neg_hi:[0,0,1]
	v_pk_fma_f32 v[66:67], v[54:55], v[92:93], v[66:67] op_sel_hi:[1,0,1]
	global_load_dwordx4 v[52:55], v[52:53], off
	v_cvt_pk_bf16_f32 v125, v68, v67
	v_pk_mul_f32 v[66:67], v[62:63], v[202:203] op_sel_hi:[0,1]
	v_pk_mul_f32 v[0:1], v[66:67], v[0:1]
	s_waitcnt vmcnt(0)
	s_nop 0
	v_pk_mul_f32 v[66:67], v[0:1], v[98:99] op_sel:[1,0] op_sel_hi:[0,0]
	v_pk_fma_f32 v[68:69], v[0:1], v[96:97], v[66:67] neg_lo:[0,0,1] neg_hi:[0,0,1]
	v_pk_fma_f32 v[0:1], v[0:1], v[96:97], v[66:67] op_sel_hi:[1,0,1]
	s_nop 0
	v_cvt_pk_bf16_f32 v126, v68, v1
	v_pk_mul_f32 v[0:1], v[62:63], v[72:73] op_sel_hi:[0,1]
	v_pk_mul_f32 v[0:1], v[0:1], v[2:3]
	s_nop 0
	v_pk_mul_f32 v[2:3], v[0:1], v[102:103] op_sel:[1,0] op_sel_hi:[0,0]
	v_pk_fma_f32 v[66:67], v[0:1], v[104:105], v[2:3] neg_lo:[0,0,1] neg_hi:[0,0,1]
	v_pk_fma_f32 v[0:1], v[0:1], v[104:105], v[2:3] op_sel_hi:[1,0,1]
	s_nop 0
	v_cvt_pk_bf16_f32 v127, v66, v1
	v_pk_mul_f32 v[0:1], v[62:63], v[200:201] op_sel_hi:[0,1]
	s_waitcnt vmcnt(10)
	v_pk_mul_f32 v[0:1], v[0:1], v[12:13]
	s_nop 0
	v_pk_mul_f32 v[2:3], v[0:1], v[108:109] op_sel:[1,0] op_sel_hi:[0,0]
	v_pk_fma_f32 v[12:13], v[0:1], v[106:107], v[2:3] neg_lo:[0,0,1] neg_hi:[0,0,1]
	v_pk_fma_f32 v[0:1], v[0:1], v[106:107], v[2:3] op_sel_hi:[1,0,1]
	s_nop 0
	v_cvt_pk_bf16_f32 v128, v12, v1
	v_pk_mul_f32 v[0:1], v[62:63], v[74:75] op_sel_hi:[0,1]
	v_pk_mul_f32 v[0:1], v[0:1], v[14:15]
	s_nop 0
	v_pk_mul_f32 v[2:3], v[0:1], v[130:131] op_sel:[1,0] op_sel_hi:[0,0]
	v_pk_fma_f32 v[12:13], v[0:1], v[132:133], v[2:3] neg_lo:[0,0,1] neg_hi:[0,0,1]
	v_pk_fma_f32 v[0:1], v[0:1], v[132:133], v[2:3] op_sel_hi:[1,0,1]
	s_nop 0
	v_cvt_pk_bf16_f32 v129, v12, v1
	v_pk_mul_f32 v[0:1], v[62:63], v[198:199] op_sel_hi:[0,1]
	v_pk_mul_f32 v[0:1], v[0:1], v[8:9]
	s_nop 0
	v_pk_mul_f32 v[2:3], v[0:1], v[142:143] op_sel:[1,0] op_sel_hi:[0,0]
	v_pk_fma_f32 v[8:9], v[0:1], v[138:139], v[2:3] neg_lo:[0,0,1] neg_hi:[0,0,1]
	v_pk_fma_f32 v[0:1], v[0:1], v[138:139], v[2:3] op_sel_hi:[1,0,1]
	s_nop 0
	v_cvt_pk_bf16_f32 v130, v8, v1
	v_pk_mul_f32 v[0:1], v[62:63], v[76:77] op_sel_hi:[0,1]
	v_pk_mul_f32 v[0:1], v[0:1], v[10:11]
	v_and_b32_e32 v10, 0xfffff0, v64
	v_pk_mul_f32 v[2:3], v[0:1], v[144:145] op_sel:[1,0] op_sel_hi:[0,0]
	v_pk_fma_f32 v[8:9], v[0:1], v[146:147], v[2:3] neg_lo:[0,0,1] neg_hi:[0,0,1]
	v_pk_fma_f32 v[0:1], v[0:1], v[146:147], v[2:3] op_sel_hi:[1,0,1]
	v_lshlrev_b32_e32 v11, 1, v64
	v_cvt_pk_bf16_f32 v131, v8, v1
	v_pk_mul_f32 v[0:1], v[62:63], v[196:197] op_sel_hi:[0,1]
	s_waitcnt vmcnt(8)
	v_pk_mul_f32 v[0:1], v[0:1], v[28:29]
	v_and_or_b32 v10, v11, 8, v10
	v_pk_mul_f32 v[2:3], v[0:1], v[150:151] op_sel:[1,0] op_sel_hi:[0,0]
	v_pk_fma_f32 v[8:9], v[0:1], v[148:149], v[2:3] neg_lo:[0,0,1] neg_hi:[0,0,1]
	v_pk_fma_f32 v[0:1], v[0:1], v[148:149], v[2:3] op_sel_hi:[1,0,1]
	v_bfe_u32 v2, v33, 5, 2
	v_cvt_pk_bf16_f32 v132, v8, v1
	v_pk_mul_f32 v[0:1], v[62:63], v[78:79] op_sel_hi:[0,1]
	v_pk_mul_f32 v[8:9], v[0:1], v[30:31]
	v_and_b32_e32 v0, 0xfffff0, v46
	v_lshlrev_b32_e32 v1, 1, v46
	v_and_or_b32 v0, v1, 8, v0
	v_lshrrev_b32_e32 v1, 1, v46
	v_lshrrev_b32_e32 v0, 1, v0
	v_and_b32_e32 v3, 3, v46
	v_lshrrev_b32_e32 v10, 1, v10
	v_or_b32_e32 v0, v0, v2
	v_and_or_b32 v1, v1, 4, v3
	v_or_b32_e32 v2, v10, v2
	v_lshlrev_b32_e32 v0, 9, v0
	v_lshlrev_b32_e32 v1, 6, v1
	v_and_b32_e32 v3, 48, v61
	v_lshlrev_b32_e32 v2, 9, v2
	v_or3_b32 v0, v0, v1, v3
	v_or3_b32 v1, v2, v1, v3
	v_add_u32_e32 v184, 0, v0
	v_add_u32_e32 v186, 0, v1
	v_lshlrev_b32_e32 v0, 8, v46
	v_and_b32_e32 v1, 0x70, v195
	v_bitop3_b32 v0, v61, v0, v1 bitop3:0xde
	v_lshlrev_b32_e32 v33, 4, v195
	v_add_u32_e32 v190, 0x10800, v0
	v_lshlrev_b32_e32 v0, 8, v64
	s_waitcnt vmcnt(3)
	ds_write_b128 v184, v[38:41]
	s_waitcnt vmcnt(2)
	ds_write_b128 v186, v[42:45]
	v_bitop3_b32 v0, v61, v0, v1 bitop3:0xde
	v_lshlrev_b32_e32 v42, 8, v191
	v_and_b32_e32 v43, 0x70, v33
	s_waitcnt vmcnt(1)
	ds_write_b128 v190, v[4:7]
	v_add_u32_e32 v192, 0x10800, v0
	v_bitop3_b32 v0, v176, v42, v43 bitop3:0xde
	v_pk_mul_f32 v[4:5], v[8:9], v[110:111] op_sel:[1,0] op_sel_hi:[0,0]
	v_add_u32_e32 v194, 0x10800, v0
	v_pk_fma_f32 v[6:7], v[8:9], v[134:135], v[4:5] neg_lo:[0,0,1] neg_hi:[0,0,1]
	v_pk_fma_f32 v[4:5], v[8:9], v[134:135], v[4:5] op_sel_hi:[1,0,1]
	s_waitcnt vmcnt(0)
	ds_write_b128 v192, v[52:55]
	s_waitcnt lgkmcnt(0)
	s_barrier
; #define SLOAD(i, k0) do { sr_[i].vs0 = *reinterpret_cast<const bf16x8*>(&Vh[(long)((k0) + sr) * LDK + sc]); sr_[i].vs1 = *reinterpret_cast<const bf16x8*>(&Vh[(long)((k0) + 32 + sr) * LDK + sc]); \
;     sr_[i].ks0 = *reinterpret_cast<const bf16x8*>(&Kh[(long)((k0) + sr) * LDK + sc]); sr_[i].ks1 = *reinterpret_cast<const bf16x8*>(&Kh[(long)((k0) + 32 + sr) * LDK + sc]); } while (0)
; #define SWRITE(b, i) do { *(bf16x8*)((char*)V_lds + (b) * SHM_V + vst0) = sr_[i].vs0;          \
;     *(bf16x8*)((char*)V_lds + (b) * SHM_V + vst1) = sr_[i].vs1; int kc = sc * 2;               \
;     *(bf16x8*)((char*)K_lds + (b) * SHM_K + KSWZ(sr, kc)) = sr_[i].ks0;                       \
;     *(bf16x8*)((char*)K_lds + (b) * SHM_K + KSWZ(32 + sr, kc)) = sr_[i].ks1; } while (0)
; #define SWAIT() asm volatile("s_waitcnt vmcnt(4)" ::: "memory")
; __device__ __forceinline__ void qkt(f32x16& p0, f32x16& p1, const bf16* Ks, const bf16x8* qr, int r32, int hi) {
;   p0 = f32x16{}; p1 = f32x16{};
; #pragma unroll
;   for (int d0 = 0; d0 < 8; ++d0) { int cb = (d0 * 16 + hi * 8) * 2;
;     bf16x8 b0 = *reinterpret_cast<const bf16x8*>((const char*)Ks + KSWZ(r32, cb));
;     bf16x8 b1 = *reinterpret_cast<const bf16x8*>((const char*)Ks + KSWZ(32 + r32, cb));
;     p0 = __builtin_amdgcn_mfma_f32_32x32x16_bf16(b0, qr[d0], p0, 0, 0, 0);
;     p1 = __builtin_amdgcn_mfma_f32_32x32x16_bf16(b1, qr[d0], p1, 0, 0, 0); }
; __device__ __forceinline__ void attn_unit_fast(const bf16* __restrict__ Qb, const bf16* __restrict__ Kh, const bf16* __restrict__ Vh, bf16* __restrict__ Ob, int NT, char* lds, int t0, const float* __restrict__ qg) {
;     ...
;   qkt(pA0, pA1, K_lds, qr, r32, hi); partialSM_fast(pA0, pA1);
;   SLOAD(SO, KVBLK); SLOAD(SE, 2 * KVBLK);
;   SWAIT(); SWRITE(1, SO); __syncthreads();
	s_add_u32 s0, s48, s0
	s_addc_u32 s1, s49, s1
	v_readfirstlane_b32 s5, v195
	v_lshrrev_b32_e32 v245, 4, v195
	v_xor_b32_e32 v244, v245, v195
	v_and_b32_e32 v244, 15, v244
	v_lshlrev_b32_e32 v244, 4, v244
	v_lshl_or_b32 v244, v245, 8, v244
	v_add_u32_e32 v244, 0x6404000, v244
	v_add_u32_e32 v245, 0x2000, v244
	v_bfe_u32 v254, v195, 2, 3
	v_bfe_u32 v253, v195, 7, 2
	v_lshl_or_b32 v254, v253, 3, v254
	v_bfe_u32 v253, v195, 5, 2
	v_lshlrev_b32_e32 v253, 6, v253
	v_lshl_or_b32 v253, v254, 8, v253
	v_and_b32_e32 v254, 3, v195
	v_lshl_or_b32 v253, v254, 4, v253
	v_add_u32_e32 v253, 0x7100000, v253
	v_add_u32_e32 v254, 0x2000, v253
	s_lshl_b32 s5, s5, 4
	s_add_u32 m0, s5, 0x0
	s_nop 0
	global_load_lds_dwordx4 v253, s[0:1]
	s_add_u32 m0, s5, 0x2000
	s_nop 0
	global_load_lds_dwordx4 v254, s[0:1]
	s_add_u32 m0, s5, 0x14800
	s_nop 0
	global_load_lds_dwordx4 v244, s[0:1]
	s_add_u32 m0, s5, 0x16800
	s_nop 0
	global_load_lds_dwordx4 v245, s[0:1]
	s_add_u32 s0, s0, 0x4000
	s_addc_u32 s1, s1, 0
	s_add_u32 m0, s5, 0x18800
	s_nop 0
	global_load_lds_dwordx4 v244, s[0:1]
	s_add_u32 m0, s5, 0x1a800
	s_nop 0
	global_load_lds_dwordx4 v245, s[0:1]
	s_add_u32 m0, s5, 0x4000
	s_nop 0
	global_load_lds_dwordx4 v253, s[0:1]
	s_add_u32 m0, s5, 0x6000
	s_nop 0
	global_load_lds_dwordx4 v254, s[0:1]
	s_add_u32 s0, s0, 0x4000
	s_addc_u32 s1, s1, 0
	s_add_u32 m0, s5, 0x1c800
	s_nop 0
	global_load_lds_dwordx4 v244, s[0:1]
	s_add_u32 m0, s5, 0x1e800
	s_nop 0
	global_load_lds_dwordx4 v245, s[0:1]
	s_add_u32 m0, s5, 0x8000
	s_nop 0
	global_load_lds_dwordx4 v253, s[0:1]
	s_add_u32 m0, s5, 0xa000
	s_nop 0
	global_load_lds_dwordx4 v254, s[0:1]
	s_add_u32 s0, s0, 0x4000
	s_addc_u32 s1, s1, 0
	ds_read_b128 v[0:3], v194
	ds_read_b128 v[28:31], v194 offset:8192
	v_cvt_pk_bf16_f32 v133, v6, v5
	v_pk_mul_f32 v[4:5], v[62:63], v[182:183] op_sel_hi:[0,1]
	v_pk_mul_f32 v[20:21], v[4:5], v[20:21]
	s_waitcnt lgkmcnt(0)
	v_mfma_f32_32x32x16_bf16 v[64:79], v[28:31], v[112:115], 0
	v_mul_f32_e64 v38, v21, v140
	v_mul_f32_e64 v39, v20, v140
	v_fma_f32 v40, v20, v136, -v38
	v_fma_f32 v41, v21, v137, -v39
	v_fma_f32 v20, v20, v136, v38
	v_fma_f32 v21, v21, v136, v39
	v_mov_b32_e32 v197, 0
	v_or_b32_e32 v20, 32, v176
	v_bitop3_b32 v20, v20, v42, v43 bitop3:0xde
	v_cvt_pk_bf16_f32 v134, v40, v21
	v_add_u32_e32 v196, 0x10800, v20
	v_pk_mul_f32 v[20:21], v[62:63], v[80:81] op_sel_hi:[0,1]
	v_pk_mul_f32 v[20:21], v[20:21], v[22:23]
	ds_read_b128 v[38:41], v196
	v_pk_mul_f32 v[22:23], v[20:21], v[60:61] op_sel:[1,0] op_sel_hi:[0,0]
	v_pk_fma_f32 v[28:29], v[20:21], v[204:205], v[22:23] neg_lo:[0,0,1] neg_hi:[0,0,1]
	v_pk_fma_f32 v[20:21], v[20:21], v[204:205], v[22:23] op_sel_hi:[1,0,1]
	v_mfma_f32_32x32x16_bf16 v[0:15], v[0:3], v[112:115], 0
	v_cvt_pk_bf16_f32 v135, v28, v21
	ds_read_b128 v[20:23], v196 offset:8192
	v_mul_f32_e64 v28, v62, v154
	v_mul_f32_e64 v29, v62, v155
	v_mul_f32_e64 v24, v28, v24
	v_mul_f32_e64 v25, v29, v25
	v_or_b32_e32 v28, 64, v176
	v_bitop3_b32 v28, v28, v42, v43 bitop3:0xde
	v_add_u32_e32 v198, 0x10800, v28
	ds_read_b128 v[28:31], v198
	s_waitcnt lgkmcnt(2)
	v_mfma_f32_32x32x16_bf16 v[0:15], v[38:41], v[116:119], v[0:15]
	v_mul_f32_e64 v38, v25, v208
	v_mul_f32_e64 v39, v24, v208
	v_mov_b32_e32 v40, v197
	v_mov_b32_e32 v41, v197
	v_mov_b32_e32 v44, v197
	v_mov_b32_e32 v45, v197
	v_mov_b32_e32 v46, v197
	v_mov_b32_e32 v47, v197
	s_waitcnt lgkmcnt(1)
	v_mfma_f32_32x32x16_bf16 v[64:79], v[20:23], v[116:119], v[64:79]
	v_fma_f32 v20, v24, v206, -v38
	v_fma_f32 v21, v25, v207, -v39
	v_fma_f32 v22, v24, v206, v38
	v_fma_f32 v23, v25, v206, v39
	v_mov_b32_e32 v52, v197
	v_cvt_pk_bf16_f32 v136, v20, v23
	v_pk_mul_f32 v[20:21], v[62:63], v[82:83] op_sel_hi:[0,1]
	v_pk_mul_f32 v[24:25], v[20:21], v[26:27]
	ds_read_b128 v[20:23], v198 offset:8192
	v_pk_mul_f32 v[26:27], v[24:25], v[210:211] op_sel:[1,0] op_sel_hi:[0,0]
	s_waitcnt lgkmcnt(1)
	v_mfma_f32_32x32x16_bf16 v[0:15], v[28:31], v[120:123], v[0:15]
	v_fma_f32 v28, v24, v216, -v26
	v_fma_f32 v29, v25, v217, -v27
	v_fma_f32 v24, v24, v216, v26
	v_fma_f32 v25, v25, v216, v27
	v_lshl_add_u64 v[30:31], v[36:37], 0, s[30:31]
	v_or_b32_e32 v24, 0x60, v176
	v_bitop3_b32 v24, v24, v42, v43 bitop3:0xde
	v_add_u32_e32 v199, 0x10800, v24
	v_cvt_pk_bf16_f32 v137, v28, v25
	ds_read_b128 v[24:27], v199
	s_waitcnt lgkmcnt(1)
	v_mfma_f32_32x32x16_bf16 v[64:79], v[20:23], v[120:123], v[64:79]
	v_mul_f32_e64 v20, v62, v152
	v_mul_f32_e64 v21, v62, v153
	v_mul_f32_e64 v16, v20, v16
	v_mul_f32_e64 v17, v21, v17
	v_lshl_add_u64 v[38:39], s[66:67], 0, v[30:31]
	v_pk_mul_f32 v[20:21], v[16:17], v[230:231] op_sel:[1,0] op_sel_hi:[0,0]
	v_pk_fma_f32 v[22:23], v[16:17], v[228:229], v[20:21] neg_lo:[0,0,1] neg_hi:[0,0,1]
	v_pk_fma_f32 v[16:17], v[16:17], v[228:229], v[20:21] op_sel_hi:[1,0,1]
	v_mov_b32_e32 v53, v197
	v_cvt_pk_bf16_f32 v138, v22, v17
	ds_read_b128 v[20:23], v199 offset:8192
	v_or_b32_e32 v16, 0x80, v176
	v_bitop3_b32 v16, v16, v42, v43 bitop3:0xde
	v_add_u32_e32 v200, 0x10800, v16
	v_lshl_add_u64 v[16:17], v[36:37], 0, s[24:25]
	s_waitcnt lgkmcnt(1)
	v_mfma_f32_32x32x16_bf16 v[0:15], v[24:27], v[124:127], v[0:15]
	ds_read_b128 v[24:27], v200
	v_lshl_add_u64 v[28:29], s[66:67], 0, v[16:17]
	v_lshl_add_u64 v[16:17], s[44:45], 0, v[16:17]
	v_lshl_add_u64 v[28:29], s[44:45], 0, v[30:31]
	v_pk_mul_f32 v[16:17], v[62:63], v[84:85] op_sel_hi:[0,1]
	v_pk_mul_f32 v[16:17], v[16:17], v[18:19]
	s_waitcnt lgkmcnt(1)
	v_mfma_f32_32x32x16_bf16 v[64:79], v[20:23], v[124:127], v[64:79]
	v_mul_f32_e64 v18, v17, v212
	v_mul_f32_e64 v19, v16, v212
	v_fma_f32 v20, v16, v164, -v18
	v_fma_f32 v21, v17, v165, -v19
	v_fma_f32 v16, v16, v164, v18
	v_fma_f32 v17, v17, v164, v19
	v_mov_b32_e32 v28, v197
	v_cvt_pk_bf16_f32 v139, v20, v17
	ds_read_b128 v[16:19], v200 offset:8192
	v_pk_mul_f32 v[20:21], v[62:63], v[100:101] op_sel_hi:[0,1]
	s_waitcnt lgkmcnt(1)
; #define QROPE(RW, GA, GB, E2, OUT) do { int pp = (8 * d0 + 4 * hi + (E2)) & 31; asm volatile("" : "+v"(pp)); const float freq = __builtin_amdgcn_exp2f(-(float)pp * (13.287712379549449f / 32.f)); \
;         float sn, cs; sincos_rev(idx * freq * INV2PI, sn, cs); const float y0 = bflo(RW) * rsc * (GA), y1 = bfhi(RW) * rsc * (GB); OUT = cvtpk(y0 * cs - y1 * sn, y0 * sn + y1 * cs); } while (0)
; __device__ __forceinline__ void partialSM_fast(f32x16& p0, f32x16& p1) {
; #pragma unroll
;   for (int r = 0; r < 16; ++r) p0[r] = __builtin_amdgcn_exp2f(p0[r]);
; }
; __device__ __forceinline__ void finishSM_fast(f32x16& p0, f32x16& p1, float& l_reg, bf16x8& pa0, bf16x8& pa1, bf16x8& pa2, bf16x8& pa3) {
; #pragma unroll
;   for (int r = 0; r < 16; ++r) p1[r] = __builtin_amdgcn_exp2f(p1[r]);
;   float ps = 0;
; #pragma unroll
;   for (int r = 0; r < 16; ++r) ps += p0[r];
; #pragma unroll
;   for (int r = 0; r < 16; ++r) ps += p1[r];
;   { auto rr = __builtin_amdgcn_permlane32_swap(__float_as_uint(ps), __float_as_uint(ps), false, false);
;     ps = __uint_as_float(rr[0]) + __uint_as_float(rr[1]); }
;   l_reg += ps;
;     ...
;   PK4(p0, 0, pa0); PK4(p0, 8, pa1); PK4(p1, 0, pa2); PK4(p1, 8, pa3);
;     ...
; }
; __device__ __forceinline__ void attn_unit_fast(const bf16* __restrict__ Qb, const bf16* __restrict__ Kh, const bf16* __restrict__ Vh, bf16* __restrict__ Ob, int NT, char* lds, int t0, const float* __restrict__ qg) {
;     ...
;     for (int d0 = 0; d0 < 8; ++d0) { const v4u rw = *reinterpret_cast<const v4u*>(Qw + d0 * 16);
;       const f32x4 g0 = *reinterpret_cast<const f32x4*>(qg + 16 * d0 + 8 * hi), g1 = *reinterpret_cast<const f32x4*>(qg + 16 * d0 + 8 * hi + 4);
;       const float idx = d0 < 4 ? frow : fcol; v4u wv;
;     ...
;       QROPE(rw.x, g0.x, g0.y, 0, wv.x); QROPE(rw.y, g0.z, g0.w, 1, wv.y); QROPE(rw.z, g1.x, g1.y, 2, wv.z); QROPE(rw.w, g1.z, g1.w, 3, wv.w);
;     ...
;       qr[d0] = __builtin_bit_cast(bf16x8, wv); }
	v_mfma_f32_32x32x16_bf16 v[0:15], v[24:27], v[128:131], v[0:15]
	v_mul_f32_e64 v24, v20, v56
	v_mul_f32_e64 v25, v21, v57
	v_or_b32_e32 v20, 0xa0, v176
	v_bitop3_b32 v20, v20, v42, v43 bitop3:0xde
	v_add_u32_e32 v201, 0x10800, v20
	ds_read_b128 v[20:23], v201
	v_pk_mul_f32 v[26:27], v[24:25], v[214:215] op_sel:[1,0] op_sel_hi:[0,0]
	v_mov_b32_e32 v29, v197
	s_waitcnt lgkmcnt(1)
	v_mfma_f32_32x32x16_bf16 v[64:79], v[16:19], v[128:131], v[64:79]
	v_fma_f32 v16, v24, v160, -v26
	v_fma_f32 v17, v25, v161, -v27
	v_fma_f32 v18, v24, v160, v26
	v_fma_f32 v19, v25, v160, v27
	v_mov_b32_e32 v30, v197
	v_cvt_pk_bf16_f32 v148, v16, v19
	v_pk_mul_f32 v[16:17], v[62:63], v[86:87] op_sel_hi:[0,1]
	v_pk_mul_f32 v[24:25], v[16:17], v[58:59]
	ds_read_b128 v[16:19], v201 offset:8192
	v_pk_mul_f32 v[26:27], v[24:25], v[222:223] op_sel:[1,0] op_sel_hi:[0,0]
	s_waitcnt lgkmcnt(1)
	v_mfma_f32_32x32x16_bf16 v[0:15], v[20:23], v[132:135], v[0:15]
	v_fma_f32 v20, v24, v224, -v26
	v_fma_f32 v21, v25, v225, -v27
	v_fma_f32 v22, v24, v224, v26
	v_fma_f32 v23, v25, v224, v27
	v_mov_b32_e32 v31, v197
	v_cvt_pk_bf16_f32 v149, v20, v23
	v_or_b32_e32 v20, 0xc0, v176
	v_bitop3_b32 v20, v20, v42, v43 bitop3:0xde
	v_add_u32_e32 v202, 0x10800, v20
	ds_read_b128 v[20:23], v202
	s_waitcnt lgkmcnt(1)
	v_mfma_f32_32x32x16_bf16 v[64:79], v[16:19], v[132:135], v[64:79]
	v_mul_f32_e64 v16, v62, v90
	v_mul_f32_e64 v17, v62, v91
	v_mul_f32_e64 v16, v16, v48
	v_mul_f32_e64 v17, v17, v49
	v_mov_b32_e32 v38, v197
	v_pk_mul_f32 v[18:19], v[16:17], v[220:221] op_sel:[1,0] op_sel_hi:[0,0]
	v_pk_fma_f32 v[24:25], v[16:17], v[226:227], v[18:19] neg_lo:[0,0,1] neg_hi:[0,0,1]
	v_pk_fma_f32 v[16:17], v[16:17], v[226:227], v[18:19] op_sel_hi:[1,0,1]
	v_mov_b32_e32 v39, v197
	v_cvt_pk_bf16_f32 v150, v24, v17
	ds_read_b128 v[16:19], v202 offset:8192
	s_waitcnt lgkmcnt(1)
	v_mfma_f32_32x32x16_bf16 v[0:15], v[20:23], v[136:139], v[0:15]
	v_mul_f32_e64 v20, v62, v88
	v_mul_f32_e64 v21, v62, v89
	v_mul_f32_e64 v24, v20, v50
	v_mul_f32_e64 v25, v21, v51
	v_or_b32_e32 v20, 0xe0, v176
	v_bitop3_b32 v20, v20, v42, v43 bitop3:0xde
	v_pk_mul_f32 v[26:27], v[24:25], v[218:219] op_sel:[1,0] op_sel_hi:[0,0]
	v_add_u32_e32 v203, 0x10800, v20
	ds_read_b128 v[20:23], v203
	s_waitcnt lgkmcnt(1)
	v_mfma_f32_32x32x16_bf16 v[64:79], v[16:19], v[136:139], v[64:79]
	v_fma_f32 v16, v24, v32, -v26
	v_fma_f32 v17, v25, v33, -v27
	v_fma_f32 v18, v24, v32, v26
	v_fma_f32 v19, v25, v32, v27
	v_lshlrev_b32_e32 v24, 3, v179
	v_cvt_pk_bf16_f32 v151, v16, v19
	v_and_b32_e32 v16, 0xc0, v33
	v_and_or_b32 v25, v24, 24, v16
	ds_read_b128 v[16:19], v203 offset:8192
	s_waitcnt lgkmcnt(1)
	v_mfma_f32_32x32x16_bf16 v[0:15], v[20:23], v[148:151], v[0:15]
	v_lshlrev_b32_e32 v20, 1, v195
	v_and_b32_e32 v20, 32, v20
	v_and_b32_e32 v21, 0x100, v24
	v_or3_b32 v24, v25, v20, v21
	v_lshl_add_u64 v[20:21], v[36:37], 0, s[38:39]
	v_lshl_add_u64 v[22:23], s[66:67], 0, v[20:21]
	v_add_u32_e32 v188, s4, v24
	s_waitcnt lgkmcnt(0)
	v_mfma_f32_32x32x16_bf16 v[64:79], v[16:19], v[148:151], v[64:79]
	v_lshl_add_u64 v[16:17], v[36:37], 0, s[34:35]
	v_lshl_add_u64 v[18:19], s[66:67], 0, v[16:17]
	v_lshl_add_u64 v[16:17], s[44:45], 0, v[16:17]
	v_lshl_add_u64 v[18:19], s[44:45], 0, v[20:21]
	s_nop 7
	s_nop 7
	v_and_b32_e32 v204, 15, v191
	v_xor_b32_e32 v204, v204, v193
	v_lshlrev_b32_e32 v204, 4, v204
	v_lshlrev_b32_e32 v205, 8, v191
	v_add_u32_e32 v205, 0x10800, v205
	v_xor_b32_e32 v194, 0x0, v204
	v_add_u32_e32 v194, v194, v205
	v_xor_b32_e32 v196, 0x20, v204
	v_add_u32_e32 v196, v196, v205
	v_xor_b32_e32 v198, 0x40, v204
	v_add_u32_e32 v198, v198, v205
	v_xor_b32_e32 v199, 0x60, v204
	v_add_u32_e32 v199, v199, v205
	v_xor_b32_e32 v200, 0x80, v204
	v_add_u32_e32 v200, v200, v205
	v_xor_b32_e32 v201, 0xa0, v204
	v_add_u32_e32 v201, v201, v205
	v_xor_b32_e32 v202, 0xc0, v204
	v_add_u32_e32 v202, v202, v205
	v_xor_b32_e32 v203, 0xe0, v204
	v_add_u32_e32 v203, v203, v205
	v_exp_f32_e32 v96, v0
	v_exp_f32_e32 v97, v1
	v_exp_f32_e32 v98, v2
	v_exp_f32_e32 v99, v3
	v_exp_f32_e32 v100, v4
	v_exp_f32_e32 v101, v5
	v_exp_f32_e32 v102, v6
	v_exp_f32_e32 v103, v7
	v_exp_f32_e32 v104, v8
	v_exp_f32_e32 v105, v9
	v_exp_f32_e32 v106, v10
	v_exp_f32_e32 v107, v11
	v_exp_f32_e32 v108, v12
	v_exp_f32_e32 v109, v13
	v_exp_f32_e32 v110, v14
	v_exp_f32_e32 v111, v15
	v_exp_f32_e32 v64, v64
	v_exp_f32_e32 v65, v65
	v_exp_f32_e32 v66, v66
	v_exp_f32_e32 v67, v67
	v_exp_f32_e32 v68, v68
	v_exp_f32_e32 v69, v69
	v_exp_f32_e32 v70, v70
	v_exp_f32_e32 v71, v71
	v_exp_f32_e32 v72, v72
	v_exp_f32_e32 v73, v73
	v_exp_f32_e32 v74, v74
	v_exp_f32_e32 v75, v75
	v_exp_f32_e32 v76, v76
	v_exp_f32_e32 v77, v77
	v_exp_f32_e32 v78, v78
	v_exp_f32_e32 v79, v79
	v_cvt_pk_bf16_f32 v140, v96, v97
	v_cvt_pk_bf16_f32 v141, v98, v99
	v_cvt_pk_bf16_f32 v142, v100, v101
	v_cvt_pk_bf16_f32 v143, v102, v103
	v_cvt_pk_bf16_f32 v144, v104, v105
	v_cvt_pk_bf16_f32 v145, v106, v107
	v_cvt_pk_bf16_f32 v146, v108, v109
	v_cvt_pk_bf16_f32 v147, v110, v111
	v_mov_b32_e32 v197, 0
	v_add_f32_e32 v238, v96, v97
	v_add_f32_e32 v238, v98, v238
	v_add_f32_e32 v238, v99, v238
	v_add_f32_e32 v238, v100, v238
	v_add_f32_e32 v238, v101, v238
	v_add_f32_e32 v238, v102, v238
	v_add_f32_e32 v238, v103, v238
	v_add_f32_e32 v238, v104, v238
	v_add_f32_e32 v238, v105, v238
	v_add_f32_e32 v238, v106, v238
	v_add_f32_e32 v238, v107, v238
	v_add_f32_e32 v238, v108, v238
	v_add_f32_e32 v238, v109, v238
	v_add_f32_e32 v238, v110, v238
	v_add_f32_e32 v238, v111, v238
	v_add_f32_e32 v197, v238, v197
	v_mov_b32_e32 v0, 0
	v_mov_b32_e32 v1, 0
	v_mov_b32_e32 v2, 0
	v_mov_b32_e32 v3, 0
	v_mov_b32_e32 v4, 0
	v_mov_b32_e32 v5, 0
	v_mov_b32_e32 v6, 0
	v_mov_b32_e32 v7, 0
	v_mov_b32_e32 v8, 0
	v_mov_b32_e32 v9, 0
	v_mov_b32_e32 v10, 0
	v_mov_b32_e32 v11, 0
	v_mov_b32_e32 v12, 0
	v_mov_b32_e32 v13, 0
	v_mov_b32_e32 v14, 0
	v_mov_b32_e32 v15, 0
	v_mov_b32_e32 v16, 0
	v_mov_b32_e32 v17, 0
	v_mov_b32_e32 v18, 0
	v_mov_b32_e32 v19, 0
	v_mov_b32_e32 v20, 0
	v_mov_b32_e32 v21, 0
	v_mov_b32_e32 v22, 0
	v_mov_b32_e32 v23, 0
	v_mov_b32_e32 v24, 0
	v_mov_b32_e32 v25, 0
	v_mov_b32_e32 v26, 0
	v_mov_b32_e32 v27, 0
	v_mov_b32_e32 v28, 0
	v_mov_b32_e32 v29, 0
	v_mov_b32_e32 v30, 0
	v_mov_b32_e32 v31, 0
	v_mov_b32_e32 v32, 0
	v_mov_b32_e32 v33, 0
	v_mov_b32_e32 v34, 0
	v_mov_b32_e32 v35, 0
	v_mov_b32_e32 v36, 0
	v_mov_b32_e32 v37, 0
	v_mov_b32_e32 v38, 0
	v_mov_b32_e32 v39, 0
	v_mov_b32_e32 v40, 0
	v_mov_b32_e32 v41, 0
	v_mov_b32_e32 v42, 0
	v_mov_b32_e32 v43, 0
	v_mov_b32_e32 v44, 0
	v_mov_b32_e32 v45, 0
	v_mov_b32_e32 v46, 0
	v_mov_b32_e32 v47, 0
	v_mov_b32_e32 v48, 0
	v_mov_b32_e32 v49, 0
	v_mov_b32_e32 v50, 0
	v_mov_b32_e32 v51, 0
	v_mov_b32_e32 v52, 0
	v_mov_b32_e32 v53, 0
	v_mov_b32_e32 v54, 0
	v_mov_b32_e32 v55, 0
	v_mov_b32_e32 v56, 0
	v_mov_b32_e32 v57, 0
	v_mov_b32_e32 v58, 0
	v_mov_b32_e32 v59, 0
	v_mov_b32_e32 v60, 0
	v_mov_b32_e32 v61, 0
	v_mov_b32_e32 v62, 0
	v_mov_b32_e32 v63, 0
	s_lshr_b32 s4, s94, 2
	s_cmp_ge_u32 s5, 0x1000
	s_cbranch_scc0 .Lattn_noprio
	s_setprio 1
; __device__ __forceinline__ void qkt(f32x16& p0, f32x16& p1, const bf16* Ks, const bf16x8* qr, int r32, int hi) {
;   p0 = f32x16{}; p1 = f32x16{};
; #pragma unroll
;   for (int d0 = 0; d0 < 8; ++d0) { int cb = (d0 * 16 + hi * 8) * 2;
;     bf16x8 b0 = *reinterpret_cast<const bf16x8*>((const char*)Ks + KSWZ(r32, cb));
;     bf16x8 b1 = *reinterpret_cast<const bf16x8*>((const char*)Ks + KSWZ(32 + r32, cb));
;     p0 = __builtin_amdgcn_mfma_f32_32x32x16_bf16(b0, qr[d0], p0, 0, 0, 0);
;     p1 = __builtin_amdgcn_mfma_f32_32x32x16_bf16(b1, qr[d0], p1, 0, 0, 0); }
; }
; __device__ __forceinline__ int v_st(int k, int c) { const int kk = (k & ~0xC) | ((k & 4) << 1) | ((k & 8) >> 1); return ((kk >> 3) * 4 + (c >> 5)) * 512 + ((kk & 7) * 32 + (c & 31)) * 2; }
; __device__ __forceinline__ int v_rd_base(int lane) { return ((lane & 3) << 3) | (((lane >> 2) & 3) << 6) | (((lane >> 4) & 1) << 5) | (((lane >> 5) & 1) << 8); }
; template <int OFF> __device__ __forceinline__ s16x4 tr_read(int vb) {
;   s16x4 r; asm volatile("ds_read_b64_tr_b16 %0, %1 offset:%2" : "=&v"(r) : "v"(vb), "i"(OFF) : "memory"); return r;
; }
; template <int D0> __device__ __forceinline__ void pv_one(f32x16& od, int vb, bf16x8 pa0, bf16x8 pa1, bf16x8 pa2, bf16x8 pa3) {
;   const s16x4 l0 = tr_read<v_rd_off(D0, 0, 0)>(vb), h0 = tr_read<v_rd_off(D0, 0, 1)>(vb), l1 = tr_read<v_rd_off(D0, 1, 0)>(vb), h1 = tr_read<v_rd_off(D0, 1, 1)>(vb);
; __device__ __forceinline__ void attn_unit_fast(const bf16* __restrict__ Qb, const bf16* __restrict__ Kh, const bf16* __restrict__ Vh, bf16* __restrict__ Ob, int NT, char* lds, int t0, const float* __restrict__ qg) {
;     ...
;   for (int j = 1; j + 1 < NT; j += 2) {
;     SBAR(); qkt(pB0, pB1, (bf16*)((char*)K_lds + SHM_K), qr, r32, hi);
;     finishSM_fast(pA0, pA1, l_reg, pa0, pa1, pa2, pa3); SBAR();
;     if (j + 2 < NT) SLOAD(SO, (j + 2) * KVBLK); SBAR();
;     pv_d0(o, vb0, pa0, pa1, pa2, pa3); partialSM_fast(pB0, pB1);
;     __syncthreads(); SWAIT(); SWRITE(0, SE);
;     __syncthreads();
;     SBAR(); qkt(pA0, pA1, K_lds, qr, r32, hi);
;     if (j + 2 == NT) MASKLAST(pA0, pA1);
;     finishSM_fast(pB0, pB1, l_reg, pa0, pa1, pa2, pa3); SBAR();
;     if (j + 3 < NT) SLOAD(SE, (j + 3) * KVBLK); SBAR();
;     pv_d0(o, vb0 + (int)SHM_V, pa0, pa1, pa2, pa3); partialSM_fast(pA0, pA1);
;     __syncthreads(); SWAIT(); SWRITE(1, SO);
;     __syncthreads();
.Lattn_noprio:
	s_waitcnt vmcnt(4)
	s_barrier
	ds_read_b128 v[206:209], v194 offset:16384
	ds_read_b128 v[210:213], v196 offset:16384
	ds_read_b128 v[214:217], v198 offset:16384
	ds_read_b128 v[218:221], v199 offset:16384
	ds_read_b128 v[160:163], v200 offset:16384
	ds_read_b128 v[164:167], v201 offset:16384
	ds_read_b128 v[168:171], v202 offset:16384
	ds_read_b128 v[172:175], v203 offset:16384
.Lattn_loop:
	s_waitcnt lgkmcnt(4)
	v_mfma_f32_32x32x16_bf16 v[96:111], v[206:209], v[112:115], 0
	ds_read_b128 v[206:209], v194 offset:24576
	v_cvt_pk_bf16_f32 v152, v64, v65
	v_cvt_pk_bf16_f32 v153, v66, v67
	v_add_f32_e32 v239, v64, v65
	v_add_f32_e32 v239, v66, v239
	v_mfma_f32_32x32x16_bf16 v[96:111], v[210:213], v[116:119], v[96:111]
	ds_read_b128 v[210:213], v196 offset:24576
	s_add_u32 m0, s5, 0x10800
	v_cvt_pk_bf16_f32 v154, v68, v69
	global_load_lds_dwordx4 v244, s[0:1]
	v_cvt_pk_bf16_f32 v155, v70, v71
	v_add_f32_e32 v239, v67, v239
	v_add_f32_e32 v239, v68, v239
	v_mfma_f32_32x32x16_bf16 v[96:111], v[214:217], v[120:123], v[96:111]
	ds_read_b128 v[214:217], v198 offset:24576
	v_add_f32_e32 v239, v69, v239
	v_add_f32_e32 v239, v70, v239
	v_mfma_f32_32x32x16_bf16 v[96:111], v[218:221], v[124:127], v[96:111]
	ds_read_b128 v[218:221], v199 offset:24576
	s_add_u32 m0, s5, 0x12800
	v_add_f32_e32 v239, v71, v239
	global_load_lds_dwordx4 v245, s[0:1]
	v_add_f32_e32 v239, v72, v239
	s_waitcnt lgkmcnt(4)
	v_mfma_f32_32x32x16_bf16 v[96:111], v[160:163], v[128:131], v[96:111]
	ds_read_b128 v[160:163], v200 offset:24576
	v_cvt_pk_bf16_f32 v156, v72, v73
	v_cvt_pk_bf16_f32 v157, v74, v75
	v_add_f32_e32 v239, v73, v239
	v_add_f32_e32 v239, v74, v239
	v_mfma_f32_32x32x16_bf16 v[96:111], v[164:167], v[132:135], v[96:111]
	ds_read_b128 v[164:167], v201 offset:24576
	v_cvt_pk_bf16_f32 v158, v76, v77
	v_cvt_pk_bf16_f32 v159, v78, v79
	v_add_f32_e32 v239, v75, v239
	v_add_f32_e32 v239, v76, v239
	v_mfma_f32_32x32x16_bf16 v[96:111], v[168:171], v[136:139], v[96:111]
	s_barrier
	ds_read_b128 v[168:171], v202 offset:24576
	v_add_f32_e32 v239, v77, v239
	v_add_f32_e32 v239, v78, v239
	v_mfma_f32_32x32x16_bf16 v[96:111], v[172:175], v[148:151], v[96:111]
	ds_read_b128 v[172:175], v203 offset:24576
	v_add_f32_e32 v239, v79, v239
	v_add_f32_e32 v197, v239, v197
	s_waitcnt lgkmcnt(4)
	v_mfma_f32_32x32x16_bf16 v[64:79], v[206:209], v[112:115], 0
	v_mfma_f32_32x32x16_bf16 v[64:79], v[210:213], v[116:119], v[64:79]
	v_mfma_f32_32x32x16_bf16 v[64:79], v[214:217], v[120:123], v[64:79]
	ds_read_b64_tr_b16 v[222:223], v188
	ds_read_b64_tr_b16 v[224:225], v188 offset:2048
	v_mfma_f32_32x32x16_bf16 v[64:79], v[218:221], v[124:127], v[64:79]
	ds_read_b64_tr_b16 v[226:227], v188 offset:512
	ds_read_b64_tr_b16 v[228:229], v188 offset:2560
	v_exp_f32_e32 v96, v96
	v_exp_f32_e32 v97, v97
	s_waitcnt lgkmcnt(4)
	v_mfma_f32_32x32x16_bf16 v[64:79], v[160:163], v[128:131], v[64:79]
	ds_read_b64_tr_b16 v[230:231], v188 offset:1024
	ds_read_b64_tr_b16 v[232:233], v188 offset:3072
	v_exp_f32_e32 v98, v98
	v_exp_f32_e32 v99, v99
	v_exp_f32_e32 v100, v100
	v_mfma_f32_32x32x16_bf16 v[64:79], v[164:167], v[132:135], v[64:79]
	ds_read_b64_tr_b16 v[234:235], v188 offset:1536
	ds_read_b64_tr_b16 v[236:237], v188 offset:3584
	v_exp_f32_e32 v101, v101
	v_exp_f32_e32 v102, v102
	v_exp_f32_e32 v103, v103
	v_mfma_f32_32x32x16_bf16 v[64:79], v[168:171], v[136:139], v[64:79]
	ds_read_b64_tr_b16 v[240:241], v188 offset:4096
	ds_read_b64_tr_b16 v[242:243], v188 offset:6144
	v_exp_f32_e32 v104, v104
	v_exp_f32_e32 v105, v105
	v_mfma_f32_32x32x16_bf16 v[64:79], v[172:175], v[148:151], v[64:79]
	ds_read_b64_tr_b16 v[180:181], v188 offset:4608
	ds_read_b64_tr_b16 v[182:183], v188 offset:6656
	v_exp_f32_e32 v106, v106
	v_exp_f32_e32 v107, v107
	s_waitcnt lgkmcnt(6)
	v_mfma_f32_32x32x16_bf16 v[0:15], v[140:143], v[222:225], v[0:15]
	ds_read_b64_tr_b16 v[222:223], v188 offset:5120
	ds_read_b64_tr_b16 v[224:225], v188 offset:7168
	v_exp_f32_e32 v108, v108
	v_exp_f32_e32 v109, v109
	v_mfma_f32_32x32x16_bf16 v[16:31], v[140:143], v[226:229], v[16:31]
	ds_read_b64_tr_b16 v[226:227], v188 offset:5632
	ds_read_b64_tr_b16 v[228:229], v188 offset:7680
	v_exp_f32_e32 v110, v110
	v_exp_f32_e32 v111, v111
	v_mfma_f32_32x32x16_bf16 v[32:47], v[140:143], v[230:233], v[32:47]
	ds_read_b64_tr_b16 v[230:231], v188 offset:8192
	ds_read_b64_tr_b16 v[232:233], v188 offset:10240
	v_exp_f32_e32 v64, v64
	v_exp_f32_e32 v65, v65
	s_waitcnt lgkmcnt(6)
	v_mfma_f32_32x32x16_bf16 v[48:63], v[140:143], v[234:237], v[48:63]
	ds_read_b64_tr_b16 v[234:235], v188 offset:8704
	ds_read_b64_tr_b16 v[236:237], v188 offset:10752
	v_exp_f32_e32 v66, v66
	v_exp_f32_e32 v67, v67
	v_mfma_f32_32x32x16_bf16 v[0:15], v[144:147], v[240:243], v[0:15]
	ds_read_b64_tr_b16 v[240:241], v188 offset:9216
	ds_read_b64_tr_b16 v[242:243], v188 offset:11264
	v_exp_f32_e32 v68, v68
	v_exp_f32_e32 v69, v69
	v_cvt_pk_bf16_f32 v140, v96, v97
	v_cvt_pk_bf16_f32 v141, v98, v99
	v_mfma_f32_32x32x16_bf16 v[16:31], v[144:147], v[180:183], v[16:31]
	ds_read_b64_tr_b16 v[180:181], v188 offset:9728
	ds_read_b64_tr_b16 v[182:183], v188 offset:11776
	v_exp_f32_e32 v70, v70
	v_exp_f32_e32 v71, v71
	v_cvt_pk_bf16_f32 v142, v100, v101
	v_cvt_pk_bf16_f32 v143, v102, v103
	s_waitcnt lgkmcnt(6)
	v_mfma_f32_32x32x16_bf16 v[32:47], v[144:147], v[222:225], v[32:47]
	ds_read_b64_tr_b16 v[222:223], v188 offset:12288
	ds_read_b64_tr_b16 v[224:225], v188 offset:14336
	v_exp_f32_e32 v72, v72
	v_exp_f32_e32 v73, v73
	v_mfma_f32_32x32x16_bf16 v[48:63], v[144:147], v[226:229], v[48:63]
	ds_read_b64_tr_b16 v[226:227], v188 offset:12800
	ds_read_b64_tr_b16 v[228:229], v188 offset:14848
	v_exp_f32_e32 v74, v74
	v_exp_f32_e32 v75, v75
	v_mfma_f32_32x32x16_bf16 v[0:15], v[152:155], v[230:233], v[0:15]
	ds_read_b64_tr_b16 v[230:231], v188 offset:13312
	ds_read_b64_tr_b16 v[232:233], v188 offset:15360
	v_exp_f32_e32 v76, v76
	v_exp_f32_e32 v77, v77
	v_cvt_pk_bf16_f32 v144, v104, v105
	v_cvt_pk_bf16_f32 v145, v106, v107
	s_waitcnt lgkmcnt(6)
	v_mfma_f32_32x32x16_bf16 v[16:31], v[152:155], v[234:237], v[16:31]
	ds_read_b64_tr_b16 v[234:235], v188 offset:13824
	ds_read_b64_tr_b16 v[236:237], v188 offset:15872
	v_exp_f32_e32 v78, v78
	v_exp_f32_e32 v79, v79
	v_cvt_pk_bf16_f32 v146, v108, v109
	v_cvt_pk_bf16_f32 v147, v110, v111
	s_waitcnt vmcnt(6)
	s_barrier
; __device__ __forceinline__ void qkt(f32x16& p0, f32x16& p1, const bf16* Ks, const bf16x8* qr, int r32, int hi) {
;   p0 = f32x16{}; p1 = f32x16{};
; #pragma unroll
;   for (int d0 = 0; d0 < 8; ++d0) { int cb = (d0 * 16 + hi * 8) * 2;
;     bf16x8 b0 = *reinterpret_cast<const bf16x8*>((const char*)Ks + KSWZ(r32, cb));
;     bf16x8 b1 = *reinterpret_cast<const bf16x8*>((const char*)Ks + KSWZ(32 + r32, cb));
;     p0 = __builtin_amdgcn_mfma_f32_32x32x16_bf16(b0, qr[d0], p0, 0, 0, 0);
;     p1 = __builtin_amdgcn_mfma_f32_32x32x16_bf16(b1, qr[d0], p1, 0, 0, 0); }
; }
; __device__ __forceinline__ int v_st(int k, int c) { const int kk = (k & ~0xC) | ((k & 4) << 1) | ((k & 8) >> 1); return ((kk >> 3) * 4 + (c >> 5)) * 512 + ((kk & 7) * 32 + (c & 31)) * 2; }
; __device__ __forceinline__ int v_rd_base(int lane) { return ((lane & 3) << 3) | (((lane >> 2) & 3) << 6) | (((lane >> 4) & 1) << 5) | (((lane >> 5) & 1) << 8); }
; template <int OFF> __device__ __forceinline__ s16x4 tr_read(int vb) {
;   s16x4 r; asm volatile("ds_read_b64_tr_b16 %0, %1 offset:%2" : "=&v"(r) : "v"(vb), "i"(OFF) : "memory"); return r;
; }
; template <int D0> __device__ __forceinline__ void pv_one(f32x16& od, int vb, bf16x8 pa0, bf16x8 pa1, bf16x8 pa2, bf16x8 pa3) {
;   const s16x4 l0 = tr_read<v_rd_off(D0, 0, 0)>(vb), h0 = tr_read<v_rd_off(D0, 0, 1)>(vb), l1 = tr_read<v_rd_off(D0, 1, 0)>(vb), h1 = tr_read<v_rd_off(D0, 1, 1)>(vb);
; __device__ __forceinline__ void attn_unit_fast(const bf16* __restrict__ Qb, const bf16* __restrict__ Kh, const bf16* __restrict__ Vh, bf16* __restrict__ Ob, int NT, char* lds, int t0, const float* __restrict__ qg) {
;     ...
;   for (int j = 1; j + 1 < NT; j += 2) {
;     SBAR(); qkt(pB0, pB1, (bf16*)((char*)K_lds + SHM_K), qr, r32, hi);
;     finishSM_fast(pA0, pA1, l_reg, pa0, pa1, pa2, pa3); SBAR();
;     if (j + 2 < NT) SLOAD(SO, (j + 2) * KVBLK); SBAR();
;     pv_d0(o, vb0, pa0, pa1, pa2, pa3); partialSM_fast(pB0, pB1);
;     __syncthreads(); SWAIT(); SWRITE(0, SE);
;     __syncthreads();
;     SBAR(); qkt(pA0, pA1, K_lds, qr, r32, hi);
;     if (j + 2 == NT) MASKLAST(pA0, pA1);
;     finishSM_fast(pB0, pB1, l_reg, pa0, pa1, pa2, pa3); SBAR();
;     if (j + 3 < NT) SLOAD(SE, (j + 3) * KVBLK); SBAR();
;     pv_d0(o, vb0 + (int)SHM_V, pa0, pa1, pa2, pa3); partialSM_fast(pA0, pA1);
;     __syncthreads(); SWAIT(); SWRITE(1, SO);
;     __syncthreads();
	v_mfma_f32_32x32x16_bf16 v[32:47], v[152:155], v[240:243], v[32:47]
	s_add_u32 m0, s5, 0xc000
	v_add_f32_e32 v238, v96, v97
	global_load_lds_dwordx4 v253, s[0:1]
	v_add_f32_e32 v238, v98, v238
	v_add_f32_e32 v238, v99, v238
	v_mfma_f32_32x32x16_bf16 v[48:63], v[152:155], v[180:183], v[48:63]
	s_add_u32 m0, s5, 0xe000
	v_add_f32_e32 v238, v100, v238
	global_load_lds_dwordx4 v254, s[0:1]
	v_add_f32_e32 v238, v101, v238
	v_add_f32_e32 v238, v102, v238
	s_add_u32 s0, s0, 0x4000
	s_addc_u32 s1, s1, 0
	s_waitcnt lgkmcnt(2)
	v_mfma_f32_32x32x16_bf16 v[0:15], v[156:159], v[222:225], v[0:15]
	v_add_f32_e32 v238, v103, v238
	v_add_f32_e32 v238, v104, v238
	v_add_f32_e32 v238, v105, v238
	ds_read_b128 v[206:209], v194 offset:32768
	ds_read_b128 v[210:213], v196 offset:32768
	v_mfma_f32_32x32x16_bf16 v[16:31], v[156:159], v[226:229], v[16:31]
	v_add_f32_e32 v238, v106, v238
	v_add_f32_e32 v238, v107, v238
	v_add_f32_e32 v238, v108, v238
	ds_read_b128 v[214:217], v198 offset:32768
	ds_read_b128 v[218:221], v199 offset:32768
	v_mfma_f32_32x32x16_bf16 v[32:47], v[156:159], v[230:233], v[32:47]
	v_add_f32_e32 v238, v109, v238
	v_add_f32_e32 v238, v110, v238
	ds_read_b128 v[160:163], v200 offset:32768
	ds_read_b128 v[164:167], v201 offset:32768
	s_waitcnt lgkmcnt(6)
	v_mfma_f32_32x32x16_bf16 v[48:63], v[156:159], v[234:237], v[48:63]
	v_add_f32_e32 v238, v111, v238
	v_add_f32_e32 v197, v238, v197
	ds_read_b128 v[168:171], v202 offset:32768
	ds_read_b128 v[172:175], v203 offset:32768
	s_waitcnt lgkmcnt(4)
	v_mfma_f32_32x32x16_bf16 v[96:111], v[206:209], v[112:115], 0
	ds_read_b128 v[206:209], v194 offset:40960
	v_cvt_pk_bf16_f32 v152, v64, v65
	v_cvt_pk_bf16_f32 v153, v66, v67
	v_add_f32_e32 v239, v64, v65
	v_add_f32_e32 v239, v66, v239
	v_mfma_f32_32x32x16_bf16 v[96:111], v[210:213], v[116:119], v[96:111]
	ds_read_b128 v[210:213], v196 offset:40960
	s_add_u32 m0, s5, 0x14800
	v_cvt_pk_bf16_f32 v154, v68, v69
	global_load_lds_dwordx4 v244, s[0:1]
	v_cvt_pk_bf16_f32 v155, v70, v71
	v_add_f32_e32 v239, v67, v239
	v_add_f32_e32 v239, v68, v239
	v_mfma_f32_32x32x16_bf16 v[96:111], v[214:217], v[120:123], v[96:111]
	ds_read_b128 v[214:217], v198 offset:40960
	v_add_f32_e32 v239, v69, v239
	v_add_f32_e32 v239, v70, v239
	v_mfma_f32_32x32x16_bf16 v[96:111], v[218:221], v[124:127], v[96:111]
	ds_read_b128 v[218:221], v199 offset:40960
	s_add_u32 m0, s5, 0x16800
	v_add_f32_e32 v239, v71, v239
	global_load_lds_dwordx4 v245, s[0:1]
	v_add_f32_e32 v239, v72, v239
	s_waitcnt lgkmcnt(4)
	v_mfma_f32_32x32x16_bf16 v[96:111], v[160:163], v[128:131], v[96:111]
	ds_read_b128 v[160:163], v200 offset:40960
	v_cvt_pk_bf16_f32 v156, v72, v73
	v_cvt_pk_bf16_f32 v157, v74, v75
	v_add_f32_e32 v239, v73, v239
	v_add_f32_e32 v239, v74, v239
	v_mfma_f32_32x32x16_bf16 v[96:111], v[164:167], v[132:135], v[96:111]
	ds_read_b128 v[164:167], v201 offset:40960
	v_cvt_pk_bf16_f32 v158, v76, v77
	v_cvt_pk_bf16_f32 v159, v78, v79
	v_add_f32_e32 v239, v75, v239
	v_add_f32_e32 v239, v76, v239
	v_mfma_f32_32x32x16_bf16 v[96:111], v[168:171], v[136:139], v[96:111]
	s_barrier
	ds_read_b128 v[168:171], v202 offset:40960
	v_add_f32_e32 v239, v77, v239
	v_add_f32_e32 v239, v78, v239
	v_mfma_f32_32x32x16_bf16 v[96:111], v[172:175], v[148:151], v[96:111]
	ds_read_b128 v[172:175], v203 offset:40960
	v_add_f32_e32 v239, v79, v239
	v_add_f32_e32 v197, v239, v197
	s_waitcnt lgkmcnt(4)
	v_mfma_f32_32x32x16_bf16 v[64:79], v[206:209], v[112:115], 0
	v_mfma_f32_32x32x16_bf16 v[64:79], v[210:213], v[116:119], v[64:79]
	v_mfma_f32_32x32x16_bf16 v[64:79], v[214:217], v[120:123], v[64:79]
	ds_read_b64_tr_b16 v[222:223], v188 offset:16384
	ds_read_b64_tr_b16 v[224:225], v188 offset:18432
	v_mfma_f32_32x32x16_bf16 v[64:79], v[218:221], v[124:127], v[64:79]
	ds_read_b64_tr_b16 v[226:227], v188 offset:16896
	ds_read_b64_tr_b16 v[228:229], v188 offset:18944
	v_exp_f32_e32 v96, v96
	v_exp_f32_e32 v97, v97
	s_waitcnt lgkmcnt(4)
	v_mfma_f32_32x32x16_bf16 v[64:79], v[160:163], v[128:131], v[64:79]
	ds_read_b64_tr_b16 v[230:231], v188 offset:17408
	ds_read_b64_tr_b16 v[232:233], v188 offset:19456
	v_exp_f32_e32 v98, v98
	v_exp_f32_e32 v99, v99
	v_exp_f32_e32 v100, v100
	v_mfma_f32_32x32x16_bf16 v[64:79], v[164:167], v[132:135], v[64:79]
	ds_read_b64_tr_b16 v[234:235], v188 offset:17920
	ds_read_b64_tr_b16 v[236:237], v188 offset:19968
	v_exp_f32_e32 v101, v101
	v_exp_f32_e32 v102, v102
	v_exp_f32_e32 v103, v103
	v_mfma_f32_32x32x16_bf16 v[64:79], v[168:171], v[136:139], v[64:79]
	ds_read_b64_tr_b16 v[240:241], v188 offset:20480
	ds_read_b64_tr_b16 v[242:243], v188 offset:22528
	v_exp_f32_e32 v104, v104
	v_exp_f32_e32 v105, v105
	v_mfma_f32_32x32x16_bf16 v[64:79], v[172:175], v[148:151], v[64:79]
	ds_read_b64_tr_b16 v[180:181], v188 offset:20992
	ds_read_b64_tr_b16 v[182:183], v188 offset:23040
	v_exp_f32_e32 v106, v106
	v_exp_f32_e32 v107, v107
	s_waitcnt lgkmcnt(6)
	v_mfma_f32_32x32x16_bf16 v[0:15], v[140:143], v[222:225], v[0:15]
	ds_read_b64_tr_b16 v[222:223], v188 offset:21504
	ds_read_b64_tr_b16 v[224:225], v188 offset:23552
	v_exp_f32_e32 v108, v108
	v_exp_f32_e32 v109, v109
	v_mfma_f32_32x32x16_bf16 v[16:31], v[140:143], v[226:229], v[16:31]
	ds_read_b64_tr_b16 v[226:227], v188 offset:22016
	ds_read_b64_tr_b16 v[228:229], v188 offset:24064
	v_exp_f32_e32 v110, v110
	v_exp_f32_e32 v111, v111
	v_mfma_f32_32x32x16_bf16 v[32:47], v[140:143], v[230:233], v[32:47]
	ds_read_b64_tr_b16 v[230:231], v188 offset:24576
	ds_read_b64_tr_b16 v[232:233], v188 offset:26624
	v_exp_f32_e32 v64, v64
	v_exp_f32_e32 v65, v65
	s_waitcnt lgkmcnt(6)
; __device__ __forceinline__ void qkt(f32x16& p0, f32x16& p1, const bf16* Ks, const bf16x8* qr, int r32, int hi) {
;   p0 = f32x16{}; p1 = f32x16{};
; #pragma unroll
;   for (int d0 = 0; d0 < 8; ++d0) { int cb = (d0 * 16 + hi * 8) * 2;
;     bf16x8 b0 = *reinterpret_cast<const bf16x8*>((const char*)Ks + KSWZ(r32, cb));
;     bf16x8 b1 = *reinterpret_cast<const bf16x8*>((const char*)Ks + KSWZ(32 + r32, cb));
;     p0 = __builtin_amdgcn_mfma_f32_32x32x16_bf16(b0, qr[d0], p0, 0, 0, 0);
;     p1 = __builtin_amdgcn_mfma_f32_32x32x16_bf16(b1, qr[d0], p1, 0, 0, 0); }
; }
; __device__ __forceinline__ int v_st(int k, int c) { const int kk = (k & ~0xC) | ((k & 4) << 1) | ((k & 8) >> 1); return ((kk >> 3) * 4 + (c >> 5)) * 512 + ((kk & 7) * 32 + (c & 31)) * 2; }
; __device__ __forceinline__ int v_rd_base(int lane) { return ((lane & 3) << 3) | (((lane >> 2) & 3) << 6) | (((lane >> 4) & 1) << 5) | (((lane >> 5) & 1) << 8); }
; template <int OFF> __device__ __forceinline__ s16x4 tr_read(int vb) {
;   s16x4 r; asm volatile("ds_read_b64_tr_b16 %0, %1 offset:%2" : "=&v"(r) : "v"(vb), "i"(OFF) : "memory"); return r;
; }
; template <int D0> __device__ __forceinline__ void pv_one(f32x16& od, int vb, bf16x8 pa0, bf16x8 pa1, bf16x8 pa2, bf16x8 pa3) {
;   const s16x4 l0 = tr_read<v_rd_off(D0, 0, 0)>(vb), h0 = tr_read<v_rd_off(D0, 0, 1)>(vb), l1 = tr_read<v_rd_off(D0, 1, 0)>(vb), h1 = tr_read<v_rd_off(D0, 1, 1)>(vb);
; __device__ __forceinline__ void attn_unit_fast(const bf16* __restrict__ Qb, const bf16* __restrict__ Kh, const bf16* __restrict__ Vh, bf16* __restrict__ Ob, int NT, char* lds, int t0, const float* __restrict__ qg) {
;     ...
;   for (int j = 1; j + 1 < NT; j += 2) {
;     SBAR(); qkt(pB0, pB1, (bf16*)((char*)K_lds + SHM_K), qr, r32, hi);
;     finishSM_fast(pA0, pA1, l_reg, pa0, pa1, pa2, pa3); SBAR();
;     if (j + 2 < NT) SLOAD(SO, (j + 2) * KVBLK); SBAR();
;     pv_d0(o, vb0, pa0, pa1, pa2, pa3); partialSM_fast(pB0, pB1);
;     __syncthreads(); SWAIT(); SWRITE(0, SE);
;     __syncthreads();
;     SBAR(); qkt(pA0, pA1, K_lds, qr, r32, hi);
;     if (j + 2 == NT) MASKLAST(pA0, pA1);
;     finishSM_fast(pB0, pB1, l_reg, pa0, pa1, pa2, pa3); SBAR();
;     if (j + 3 < NT) SLOAD(SE, (j + 3) * KVBLK); SBAR();
;     pv_d0(o, vb0 + (int)SHM_V, pa0, pa1, pa2, pa3); partialSM_fast(pA0, pA1);
;     __syncthreads(); SWAIT(); SWRITE(1, SO);
;     __syncthreads();
	v_mfma_f32_32x32x16_bf16 v[48:63], v[140:143], v[234:237], v[48:63]
	ds_read_b64_tr_b16 v[234:235], v188 offset:25088
	ds_read_b64_tr_b16 v[236:237], v188 offset:27136
	v_exp_f32_e32 v66, v66
	v_exp_f32_e32 v67, v67
	v_mfma_f32_32x32x16_bf16 v[0:15], v[144:147], v[240:243], v[0:15]
	ds_read_b64_tr_b16 v[240:241], v188 offset:25600
	ds_read_b64_tr_b16 v[242:243], v188 offset:27648
	v_exp_f32_e32 v68, v68
	v_exp_f32_e32 v69, v69
	v_cvt_pk_bf16_f32 v140, v96, v97
	v_cvt_pk_bf16_f32 v141, v98, v99
	v_mfma_f32_32x32x16_bf16 v[16:31], v[144:147], v[180:183], v[16:31]
	ds_read_b64_tr_b16 v[180:181], v188 offset:26112
	ds_read_b64_tr_b16 v[182:183], v188 offset:28160
	v_exp_f32_e32 v70, v70
	v_exp_f32_e32 v71, v71
	v_cvt_pk_bf16_f32 v142, v100, v101
	v_cvt_pk_bf16_f32 v143, v102, v103
	s_waitcnt lgkmcnt(6)
	v_mfma_f32_32x32x16_bf16 v[32:47], v[144:147], v[222:225], v[32:47]
	ds_read_b64_tr_b16 v[222:223], v188 offset:28672
	ds_read_b64_tr_b16 v[224:225], v188 offset:30720
	v_exp_f32_e32 v72, v72
	v_exp_f32_e32 v73, v73
	v_mfma_f32_32x32x16_bf16 v[48:63], v[144:147], v[226:229], v[48:63]
	ds_read_b64_tr_b16 v[226:227], v188 offset:29184
	ds_read_b64_tr_b16 v[228:229], v188 offset:31232
	v_exp_f32_e32 v74, v74
	v_exp_f32_e32 v75, v75
	v_mfma_f32_32x32x16_bf16 v[0:15], v[152:155], v[230:233], v[0:15]
	ds_read_b64_tr_b16 v[230:231], v188 offset:29696
	ds_read_b64_tr_b16 v[232:233], v188 offset:31744
	v_exp_f32_e32 v76, v76
	v_exp_f32_e32 v77, v77
	v_cvt_pk_bf16_f32 v144, v104, v105
	v_cvt_pk_bf16_f32 v145, v106, v107
	s_waitcnt lgkmcnt(6)
	v_mfma_f32_32x32x16_bf16 v[16:31], v[152:155], v[234:237], v[16:31]
	ds_read_b64_tr_b16 v[234:235], v188 offset:30208
	ds_read_b64_tr_b16 v[236:237], v188 offset:32256
	v_exp_f32_e32 v78, v78
	v_exp_f32_e32 v79, v79
	v_cvt_pk_bf16_f32 v146, v108, v109
	v_cvt_pk_bf16_f32 v147, v110, v111
	s_waitcnt vmcnt(6)
	s_barrier
	v_mfma_f32_32x32x16_bf16 v[32:47], v[152:155], v[240:243], v[32:47]
	s_add_u32 m0, s5, 0x0
	v_add_f32_e32 v238, v96, v97
	global_load_lds_dwordx4 v253, s[0:1]
	v_add_f32_e32 v238, v98, v238
	v_add_f32_e32 v238, v99, v238
	v_mfma_f32_32x32x16_bf16 v[48:63], v[152:155], v[180:183], v[48:63]
	s_add_u32 m0, s5, 0x2000
	v_add_f32_e32 v238, v100, v238
	global_load_lds_dwordx4 v254, s[0:1]
	v_add_f32_e32 v238, v101, v238
	v_add_f32_e32 v238, v102, v238
	s_add_u32 s0, s0, 0x4000
	s_addc_u32 s1, s1, 0
	s_waitcnt lgkmcnt(2)
	v_mfma_f32_32x32x16_bf16 v[0:15], v[156:159], v[222:225], v[0:15]
	v_add_f32_e32 v238, v103, v238
	v_add_f32_e32 v238, v104, v238
	v_add_f32_e32 v238, v105, v238
	ds_read_b128 v[206:209], v194 offset:49152
	ds_read_b128 v[210:213], v196 offset:49152
	v_mfma_f32_32x32x16_bf16 v[16:31], v[156:159], v[226:229], v[16:31]
	v_add_f32_e32 v238, v106, v238
	v_add_f32_e32 v238, v107, v238
	v_add_f32_e32 v238, v108, v238
	ds_read_b128 v[214:217], v198 offset:49152
	ds_read_b128 v[218:221], v199 offset:49152
	v_mfma_f32_32x32x16_bf16 v[32:47], v[156:159], v[230:233], v[32:47]
	v_add_f32_e32 v238, v109, v238
	v_add_f32_e32 v238, v110, v238
	ds_read_b128 v[160:163], v200 offset:49152
	ds_read_b128 v[164:167], v201 offset:49152
	s_waitcnt lgkmcnt(6)
	v_mfma_f32_32x32x16_bf16 v[48:63], v[156:159], v[234:237], v[48:63]
	v_add_f32_e32 v238, v111, v238
	v_add_f32_e32 v197, v238, v197
	ds_read_b128 v[168:171], v202 offset:49152
	ds_read_b128 v[172:175], v203 offset:49152
	s_waitcnt lgkmcnt(4)
	v_mfma_f32_32x32x16_bf16 v[96:111], v[206:209], v[112:115], 0
	ds_read_b128 v[206:209], v194 offset:57344
	v_cvt_pk_bf16_f32 v152, v64, v65
	v_cvt_pk_bf16_f32 v153, v66, v67
	v_add_f32_e32 v239, v64, v65
	v_add_f32_e32 v239, v66, v239
	v_mfma_f32_32x32x16_bf16 v[96:111], v[210:213], v[116:119], v[96:111]
	ds_read_b128 v[210:213], v196 offset:57344
	s_add_u32 m0, s5, 0x18800
	v_cvt_pk_bf16_f32 v154, v68, v69
	global_load_lds_dwordx4 v244, s[0:1]
	v_cvt_pk_bf16_f32 v155, v70, v71
	v_add_f32_e32 v239, v67, v239
	v_add_f32_e32 v239, v68, v239
	v_mfma_f32_32x32x16_bf16 v[96:111], v[214:217], v[120:123], v[96:111]
	ds_read_b128 v[214:217], v198 offset:57344
	v_add_f32_e32 v239, v69, v239
	v_add_f32_e32 v239, v70, v239
	v_mfma_f32_32x32x16_bf16 v[96:111], v[218:221], v[124:127], v[96:111]
	ds_read_b128 v[218:221], v199 offset:57344
	s_add_u32 m0, s5, 0x1a800
	v_add_f32_e32 v239, v71, v239
	global_load_lds_dwordx4 v245, s[0:1]
	v_add_f32_e32 v239, v72, v239
	s_waitcnt lgkmcnt(4)
	v_mfma_f32_32x32x16_bf16 v[96:111], v[160:163], v[128:131], v[96:111]
	ds_read_b128 v[160:163], v200 offset:57344
	v_cvt_pk_bf16_f32 v156, v72, v73
	v_cvt_pk_bf16_f32 v157, v74, v75
	v_add_f32_e32 v239, v73, v239
	v_add_f32_e32 v239, v74, v239
	v_mfma_f32_32x32x16_bf16 v[96:111], v[164:167], v[132:135], v[96:111]
	ds_read_b128 v[164:167], v201 offset:57344
	v_cvt_pk_bf16_f32 v158, v76, v77
	v_cvt_pk_bf16_f32 v159, v78, v79
	v_add_f32_e32 v239, v75, v239
	v_add_f32_e32 v239, v76, v239
	v_mfma_f32_32x32x16_bf16 v[96:111], v[168:171], v[136:139], v[96:111]
	s_barrier
; __device__ __forceinline__ void qkt(f32x16& p0, f32x16& p1, const bf16* Ks, const bf16x8* qr, int r32, int hi) {
;   p0 = f32x16{}; p1 = f32x16{};
; #pragma unroll
;   for (int d0 = 0; d0 < 8; ++d0) { int cb = (d0 * 16 + hi * 8) * 2;
;     bf16x8 b0 = *reinterpret_cast<const bf16x8*>((const char*)Ks + KSWZ(r32, cb));
;     bf16x8 b1 = *reinterpret_cast<const bf16x8*>((const char*)Ks + KSWZ(32 + r32, cb));
;     p0 = __builtin_amdgcn_mfma_f32_32x32x16_bf16(b0, qr[d0], p0, 0, 0, 0);
;     p1 = __builtin_amdgcn_mfma_f32_32x32x16_bf16(b1, qr[d0], p1, 0, 0, 0); }
; }
; __device__ __forceinline__ int v_st(int k, int c) { const int kk = (k & ~0xC) | ((k & 4) << 1) | ((k & 8) >> 1); return ((kk >> 3) * 4 + (c >> 5)) * 512 + ((kk & 7) * 32 + (c & 31)) * 2; }
; __device__ __forceinline__ int v_rd_base(int lane) { return ((lane & 3) << 3) | (((lane >> 2) & 3) << 6) | (((lane >> 4) & 1) << 5) | (((lane >> 5) & 1) << 8); }
; template <int OFF> __device__ __forceinline__ s16x4 tr_read(int vb) {
;   s16x4 r; asm volatile("ds_read_b64_tr_b16 %0, %1 offset:%2" : "=&v"(r) : "v"(vb), "i"(OFF) : "memory"); return r;
; }
; template <int D0> __device__ __forceinline__ void pv_one(f32x16& od, int vb, bf16x8 pa0, bf16x8 pa1, bf16x8 pa2, bf16x8 pa3) {
;   const s16x4 l0 = tr_read<v_rd_off(D0, 0, 0)>(vb), h0 = tr_read<v_rd_off(D0, 0, 1)>(vb), l1 = tr_read<v_rd_off(D0, 1, 0)>(vb), h1 = tr_read<v_rd_off(D0, 1, 1)>(vb);
; __device__ __forceinline__ void attn_unit_fast(const bf16* __restrict__ Qb, const bf16* __restrict__ Kh, const bf16* __restrict__ Vh, bf16* __restrict__ Ob, int NT, char* lds, int t0, const float* __restrict__ qg) {
;     ...
;   for (int j = 1; j + 1 < NT; j += 2) {
;     SBAR(); qkt(pB0, pB1, (bf16*)((char*)K_lds + SHM_K), qr, r32, hi);
;     finishSM_fast(pA0, pA1, l_reg, pa0, pa1, pa2, pa3); SBAR();
;     if (j + 2 < NT) SLOAD(SO, (j + 2) * KVBLK); SBAR();
;     pv_d0(o, vb0, pa0, pa1, pa2, pa3); partialSM_fast(pB0, pB1);
;     __syncthreads(); SWAIT(); SWRITE(0, SE);
;     __syncthreads();
;     SBAR(); qkt(pA0, pA1, K_lds, qr, r32, hi);
;     if (j + 2 == NT) MASKLAST(pA0, pA1);
;     finishSM_fast(pB0, pB1, l_reg, pa0, pa1, pa2, pa3); SBAR();
;     if (j + 3 < NT) SLOAD(SE, (j + 3) * KVBLK); SBAR();
;     pv_d0(o, vb0 + (int)SHM_V, pa0, pa1, pa2, pa3); partialSM_fast(pA0, pA1);
;     __syncthreads(); SWAIT(); SWRITE(1, SO);
;     __syncthreads();
	ds_read_b128 v[168:171], v202 offset:57344
	v_add_f32_e32 v239, v77, v239
	v_add_f32_e32 v239, v78, v239
	v_mfma_f32_32x32x16_bf16 v[96:111], v[172:175], v[148:151], v[96:111]
	ds_read_b128 v[172:175], v203 offset:57344
	v_add_f32_e32 v239, v79, v239
	v_add_f32_e32 v197, v239, v197
	s_waitcnt lgkmcnt(4)
	v_mfma_f32_32x32x16_bf16 v[64:79], v[206:209], v[112:115], 0
	v_mfma_f32_32x32x16_bf16 v[64:79], v[210:213], v[116:119], v[64:79]
	v_mfma_f32_32x32x16_bf16 v[64:79], v[214:217], v[120:123], v[64:79]
	ds_read_b64_tr_b16 v[222:223], v188 offset:32768
	ds_read_b64_tr_b16 v[224:225], v188 offset:34816
	v_mfma_f32_32x32x16_bf16 v[64:79], v[218:221], v[124:127], v[64:79]
	ds_read_b64_tr_b16 v[226:227], v188 offset:33280
	ds_read_b64_tr_b16 v[228:229], v188 offset:35328
	v_exp_f32_e32 v96, v96
	v_exp_f32_e32 v97, v97
	s_waitcnt lgkmcnt(4)
	v_mfma_f32_32x32x16_bf16 v[64:79], v[160:163], v[128:131], v[64:79]
	ds_read_b64_tr_b16 v[230:231], v188 offset:33792
	ds_read_b64_tr_b16 v[232:233], v188 offset:35840
	v_exp_f32_e32 v98, v98
	v_exp_f32_e32 v99, v99
	v_exp_f32_e32 v100, v100
	v_mfma_f32_32x32x16_bf16 v[64:79], v[164:167], v[132:135], v[64:79]
	ds_read_b64_tr_b16 v[234:235], v188 offset:34304
	ds_read_b64_tr_b16 v[236:237], v188 offset:36352
	v_exp_f32_e32 v101, v101
	v_exp_f32_e32 v102, v102
	v_exp_f32_e32 v103, v103
	v_mfma_f32_32x32x16_bf16 v[64:79], v[168:171], v[136:139], v[64:79]
	ds_read_b64_tr_b16 v[240:241], v188 offset:36864
	ds_read_b64_tr_b16 v[242:243], v188 offset:38912
	v_exp_f32_e32 v104, v104
	v_exp_f32_e32 v105, v105
	v_mfma_f32_32x32x16_bf16 v[64:79], v[172:175], v[148:151], v[64:79]
	ds_read_b64_tr_b16 v[180:181], v188 offset:37376
	ds_read_b64_tr_b16 v[182:183], v188 offset:39424
	v_exp_f32_e32 v106, v106
	v_exp_f32_e32 v107, v107
	s_waitcnt lgkmcnt(6)
	v_mfma_f32_32x32x16_bf16 v[0:15], v[140:143], v[222:225], v[0:15]
	ds_read_b64_tr_b16 v[222:223], v188 offset:37888
	ds_read_b64_tr_b16 v[224:225], v188 offset:39936
	v_exp_f32_e32 v108, v108
	v_exp_f32_e32 v109, v109
	v_mfma_f32_32x32x16_bf16 v[16:31], v[140:143], v[226:229], v[16:31]
	ds_read_b64_tr_b16 v[226:227], v188 offset:38400
	ds_read_b64_tr_b16 v[228:229], v188 offset:40448
	v_exp_f32_e32 v110, v110
	v_exp_f32_e32 v111, v111
	v_mfma_f32_32x32x16_bf16 v[32:47], v[140:143], v[230:233], v[32:47]
	ds_read_b64_tr_b16 v[230:231], v188 offset:40960
	ds_read_b64_tr_b16 v[232:233], v188 offset:43008
	v_exp_f32_e32 v64, v64
	v_exp_f32_e32 v65, v65
	s_waitcnt lgkmcnt(6)
	v_mfma_f32_32x32x16_bf16 v[48:63], v[140:143], v[234:237], v[48:63]
	ds_read_b64_tr_b16 v[234:235], v188 offset:41472
	ds_read_b64_tr_b16 v[236:237], v188 offset:43520
	v_exp_f32_e32 v66, v66
	v_exp_f32_e32 v67, v67
	v_mfma_f32_32x32x16_bf16 v[0:15], v[144:147], v[240:243], v[0:15]
	ds_read_b64_tr_b16 v[240:241], v188 offset:41984
	ds_read_b64_tr_b16 v[242:243], v188 offset:44032
	v_exp_f32_e32 v68, v68
	v_exp_f32_e32 v69, v69
	v_cvt_pk_bf16_f32 v140, v96, v97
	v_cvt_pk_bf16_f32 v141, v98, v99
	v_mfma_f32_32x32x16_bf16 v[16:31], v[144:147], v[180:183], v[16:31]
	ds_read_b64_tr_b16 v[180:181], v188 offset:42496
	ds_read_b64_tr_b16 v[182:183], v188 offset:44544
	v_exp_f32_e32 v70, v70
	v_exp_f32_e32 v71, v71
	v_cvt_pk_bf16_f32 v142, v100, v101
	v_cvt_pk_bf16_f32 v143, v102, v103
	s_waitcnt lgkmcnt(6)
	v_mfma_f32_32x32x16_bf16 v[32:47], v[144:147], v[222:225], v[32:47]
	ds_read_b64_tr_b16 v[222:223], v188 offset:45056
	ds_read_b64_tr_b16 v[224:225], v188 offset:47104
	v_exp_f32_e32 v72, v72
	v_exp_f32_e32 v73, v73
	v_mfma_f32_32x32x16_bf16 v[48:63], v[144:147], v[226:229], v[48:63]
	ds_read_b64_tr_b16 v[226:227], v188 offset:45568
	ds_read_b64_tr_b16 v[228:229], v188 offset:47616
	v_exp_f32_e32 v74, v74
	v_exp_f32_e32 v75, v75
	v_mfma_f32_32x32x16_bf16 v[0:15], v[152:155], v[230:233], v[0:15]
	ds_read_b64_tr_b16 v[230:231], v188 offset:46080
	ds_read_b64_tr_b16 v[232:233], v188 offset:48128
	v_exp_f32_e32 v76, v76
	v_exp_f32_e32 v77, v77
	v_cvt_pk_bf16_f32 v144, v104, v105
	v_cvt_pk_bf16_f32 v145, v106, v107
	s_waitcnt lgkmcnt(6)
	v_mfma_f32_32x32x16_bf16 v[16:31], v[152:155], v[234:237], v[16:31]
	ds_read_b64_tr_b16 v[234:235], v188 offset:46592
	ds_read_b64_tr_b16 v[236:237], v188 offset:48640
	v_exp_f32_e32 v78, v78
	v_exp_f32_e32 v79, v79
	v_cvt_pk_bf16_f32 v146, v108, v109
	v_cvt_pk_bf16_f32 v147, v110, v111
	s_waitcnt vmcnt(6)
	s_barrier
; __device__ __forceinline__ void qkt(f32x16& p0, f32x16& p1, const bf16* Ks, const bf16x8* qr, int r32, int hi) {
;   p0 = f32x16{}; p1 = f32x16{};
; #pragma unroll
;   for (int d0 = 0; d0 < 8; ++d0) { int cb = (d0 * 16 + hi * 8) * 2;
;     bf16x8 b0 = *reinterpret_cast<const bf16x8*>((const char*)Ks + KSWZ(r32, cb));
;     bf16x8 b1 = *reinterpret_cast<const bf16x8*>((const char*)Ks + KSWZ(32 + r32, cb));
;     p0 = __builtin_amdgcn_mfma_f32_32x32x16_bf16(b0, qr[d0], p0, 0, 0, 0);
;     p1 = __builtin_amdgcn_mfma_f32_32x32x16_bf16(b1, qr[d0], p1, 0, 0, 0); }
; }
; __device__ __forceinline__ int v_st(int k, int c) { const int kk = (k & ~0xC) | ((k & 4) << 1) | ((k & 8) >> 1); return ((kk >> 3) * 4 + (c >> 5)) * 512 + ((kk & 7) * 32 + (c & 31)) * 2; }
; __device__ __forceinline__ int v_rd_base(int lane) { return ((lane & 3) << 3) | (((lane >> 2) & 3) << 6) | (((lane >> 4) & 1) << 5) | (((lane >> 5) & 1) << 8); }
; template <int OFF> __device__ __forceinline__ s16x4 tr_read(int vb) {
;   s16x4 r; asm volatile("ds_read_b64_tr_b16 %0, %1 offset:%2" : "=&v"(r) : "v"(vb), "i"(OFF) : "memory"); return r;
; }
; template <int D0> __device__ __forceinline__ void pv_one(f32x16& od, int vb, bf16x8 pa0, bf16x8 pa1, bf16x8 pa2, bf16x8 pa3) {
;   const s16x4 l0 = tr_read<v_rd_off(D0, 0, 0)>(vb), h0 = tr_read<v_rd_off(D0, 0, 1)>(vb), l1 = tr_read<v_rd_off(D0, 1, 0)>(vb), h1 = tr_read<v_rd_off(D0, 1, 1)>(vb);
; __device__ __forceinline__ void attn_unit_fast(const bf16* __restrict__ Qb, const bf16* __restrict__ Kh, const bf16* __restrict__ Vh, bf16* __restrict__ Ob, int NT, char* lds, int t0, const float* __restrict__ qg) {
;     ...
;   for (int j = 1; j + 1 < NT; j += 2) {
;     SBAR(); qkt(pB0, pB1, (bf16*)((char*)K_lds + SHM_K), qr, r32, hi);
;     finishSM_fast(pA0, pA1, l_reg, pa0, pa1, pa2, pa3); SBAR();
;     if (j + 2 < NT) SLOAD(SO, (j + 2) * KVBLK); SBAR();
;     pv_d0(o, vb0, pa0, pa1, pa2, pa3); partialSM_fast(pB0, pB1);
;     __syncthreads(); SWAIT(); SWRITE(0, SE);
;     __syncthreads();
;     SBAR(); qkt(pA0, pA1, K_lds, qr, r32, hi);
;     if (j + 2 == NT) MASKLAST(pA0, pA1);
;     finishSM_fast(pB0, pB1, l_reg, pa0, pa1, pa2, pa3); SBAR();
;     if (j + 3 < NT) SLOAD(SE, (j + 3) * KVBLK); SBAR();
;     pv_d0(o, vb0 + (int)SHM_V, pa0, pa1, pa2, pa3); partialSM_fast(pA0, pA1);
;     __syncthreads(); SWAIT(); SWRITE(1, SO);
;     __syncthreads();
	v_mfma_f32_32x32x16_bf16 v[32:47], v[152:155], v[240:243], v[32:47]
	s_add_u32 m0, s5, 0x4000
	v_add_f32_e32 v238, v96, v97
	global_load_lds_dwordx4 v253, s[0:1]
	v_add_f32_e32 v238, v98, v238
	v_add_f32_e32 v238, v99, v238
	v_mfma_f32_32x32x16_bf16 v[48:63], v[152:155], v[180:183], v[48:63]
	s_add_u32 m0, s5, 0x6000
	v_add_f32_e32 v238, v100, v238
	global_load_lds_dwordx4 v254, s[0:1]
	v_add_f32_e32 v238, v101, v238
	v_add_f32_e32 v238, v102, v238
	s_add_u32 s0, s0, 0x4000
	s_addc_u32 s1, s1, 0
	s_waitcnt lgkmcnt(2)
	v_mfma_f32_32x32x16_bf16 v[0:15], v[156:159], v[222:225], v[0:15]
	v_add_f32_e32 v238, v103, v238
	v_add_f32_e32 v238, v104, v238
	v_add_f32_e32 v238, v105, v238
	ds_read_b128 v[206:209], v194
	ds_read_b128 v[210:213], v196
	v_mfma_f32_32x32x16_bf16 v[16:31], v[156:159], v[226:229], v[16:31]
	v_add_f32_e32 v238, v106, v238
	v_add_f32_e32 v238, v107, v238
	v_add_f32_e32 v238, v108, v238
	ds_read_b128 v[214:217], v198
	ds_read_b128 v[218:221], v199
	v_mfma_f32_32x32x16_bf16 v[32:47], v[156:159], v[230:233], v[32:47]
	v_add_f32_e32 v238, v109, v238
	v_add_f32_e32 v238, v110, v238
	ds_read_b128 v[160:163], v200
	ds_read_b128 v[164:167], v201
	s_waitcnt lgkmcnt(6)
	v_mfma_f32_32x32x16_bf16 v[48:63], v[156:159], v[234:237], v[48:63]
	v_add_f32_e32 v238, v111, v238
	v_add_f32_e32 v197, v238, v197
	ds_read_b128 v[168:171], v202
	ds_read_b128 v[172:175], v203
	s_waitcnt lgkmcnt(4)
	v_mfma_f32_32x32x16_bf16 v[96:111], v[206:209], v[112:115], 0
	ds_read_b128 v[206:209], v194 offset:8192
	v_cvt_pk_bf16_f32 v152, v64, v65
	v_cvt_pk_bf16_f32 v153, v66, v67
	v_add_f32_e32 v239, v64, v65
	v_add_f32_e32 v239, v66, v239
	v_mfma_f32_32x32x16_bf16 v[96:111], v[210:213], v[116:119], v[96:111]
	ds_read_b128 v[210:213], v196 offset:8192
	s_add_u32 m0, s5, 0x1c800
	v_cvt_pk_bf16_f32 v154, v68, v69
	global_load_lds_dwordx4 v244, s[0:1]
	v_cvt_pk_bf16_f32 v155, v70, v71
	v_add_f32_e32 v239, v67, v239
	v_add_f32_e32 v239, v68, v239
	v_mfma_f32_32x32x16_bf16 v[96:111], v[214:217], v[120:123], v[96:111]
	ds_read_b128 v[214:217], v198 offset:8192
	v_add_f32_e32 v239, v69, v239
	v_add_f32_e32 v239, v70, v239
	v_mfma_f32_32x32x16_bf16 v[96:111], v[218:221], v[124:127], v[96:111]
	ds_read_b128 v[218:221], v199 offset:8192
	s_add_u32 m0, s5, 0x1e800
	v_add_f32_e32 v239, v71, v239
	global_load_lds_dwordx4 v245, s[0:1]
	v_add_f32_e32 v239, v72, v239
	s_waitcnt lgkmcnt(4)
	v_mfma_f32_32x32x16_bf16 v[96:111], v[160:163], v[128:131], v[96:111]
	ds_read_b128 v[160:163], v200 offset:8192
	v_cvt_pk_bf16_f32 v156, v72, v73
	v_cvt_pk_bf16_f32 v157, v74, v75
	v_add_f32_e32 v239, v73, v239
	v_add_f32_e32 v239, v74, v239
	v_mfma_f32_32x32x16_bf16 v[96:111], v[164:167], v[132:135], v[96:111]
	ds_read_b128 v[164:167], v201 offset:8192
	v_cvt_pk_bf16_f32 v158, v76, v77
	v_cvt_pk_bf16_f32 v159, v78, v79
	v_add_f32_e32 v239, v75, v239
	v_add_f32_e32 v239, v76, v239
	v_mfma_f32_32x32x16_bf16 v[96:111], v[168:171], v[136:139], v[96:111]
	s_barrier
	ds_read_b128 v[168:171], v202 offset:8192
	v_add_f32_e32 v239, v77, v239
	v_add_f32_e32 v239, v78, v239
	v_mfma_f32_32x32x16_bf16 v[96:111], v[172:175], v[148:151], v[96:111]
	ds_read_b128 v[172:175], v203 offset:8192
	v_add_f32_e32 v239, v79, v239
	v_add_f32_e32 v197, v239, v197
	s_waitcnt lgkmcnt(4)
	v_mfma_f32_32x32x16_bf16 v[64:79], v[206:209], v[112:115], 0
	v_mfma_f32_32x32x16_bf16 v[64:79], v[210:213], v[116:119], v[64:79]
	v_mfma_f32_32x32x16_bf16 v[64:79], v[214:217], v[120:123], v[64:79]
	ds_read_b64_tr_b16 v[222:223], v188 offset:49152
	ds_read_b64_tr_b16 v[224:225], v188 offset:51200
	v_mfma_f32_32x32x16_bf16 v[64:79], v[218:221], v[124:127], v[64:79]
	ds_read_b64_tr_b16 v[226:227], v188 offset:49664
	ds_read_b64_tr_b16 v[228:229], v188 offset:51712
	v_exp_f32_e32 v96, v96
	v_exp_f32_e32 v97, v97
	s_waitcnt lgkmcnt(4)
	v_mfma_f32_32x32x16_bf16 v[64:79], v[160:163], v[128:131], v[64:79]
	ds_read_b64_tr_b16 v[230:231], v188 offset:50176
	ds_read_b64_tr_b16 v[232:233], v188 offset:52224
	v_exp_f32_e32 v98, v98
	v_exp_f32_e32 v99, v99
	v_exp_f32_e32 v100, v100
	v_mfma_f32_32x32x16_bf16 v[64:79], v[164:167], v[132:135], v[64:79]
	ds_read_b64_tr_b16 v[234:235], v188 offset:50688
	ds_read_b64_tr_b16 v[236:237], v188 offset:52736
	v_exp_f32_e32 v101, v101
	v_exp_f32_e32 v102, v102
	v_exp_f32_e32 v103, v103
	v_mfma_f32_32x32x16_bf16 v[64:79], v[168:171], v[136:139], v[64:79]
	ds_read_b64_tr_b16 v[240:241], v188 offset:53248
	ds_read_b64_tr_b16 v[242:243], v188 offset:55296
	v_exp_f32_e32 v104, v104
	v_exp_f32_e32 v105, v105
	v_mfma_f32_32x32x16_bf16 v[64:79], v[172:175], v[148:151], v[64:79]
	ds_read_b64_tr_b16 v[180:181], v188 offset:53760
	ds_read_b64_tr_b16 v[182:183], v188 offset:55808
	v_exp_f32_e32 v106, v106
	v_exp_f32_e32 v107, v107
	s_waitcnt lgkmcnt(6)
	v_mfma_f32_32x32x16_bf16 v[0:15], v[140:143], v[222:225], v[0:15]
	ds_read_b64_tr_b16 v[222:223], v188 offset:54272
	ds_read_b64_tr_b16 v[224:225], v188 offset:56320
	v_exp_f32_e32 v108, v108
	v_exp_f32_e32 v109, v109
	v_mfma_f32_32x32x16_bf16 v[16:31], v[140:143], v[226:229], v[16:31]
	ds_read_b64_tr_b16 v[226:227], v188 offset:54784
	ds_read_b64_tr_b16 v[228:229], v188 offset:56832
	v_exp_f32_e32 v110, v110
	v_exp_f32_e32 v111, v111
	v_mfma_f32_32x32x16_bf16 v[32:47], v[140:143], v[230:233], v[32:47]
	ds_read_b64_tr_b16 v[230:231], v188 offset:57344
	ds_read_b64_tr_b16 v[232:233], v188 offset:59392
	v_exp_f32_e32 v64, v64
	v_exp_f32_e32 v65, v65
	s_waitcnt lgkmcnt(6)
; __device__ __forceinline__ void qkt(f32x16& p0, f32x16& p1, const bf16* Ks, const bf16x8* qr, int r32, int hi) {
;   p0 = f32x16{}; p1 = f32x16{};
; #pragma unroll
;   for (int d0 = 0; d0 < 8; ++d0) { int cb = (d0 * 16 + hi * 8) * 2;
;     bf16x8 b0 = *reinterpret_cast<const bf16x8*>((const char*)Ks + KSWZ(r32, cb));
;     bf16x8 b1 = *reinterpret_cast<const bf16x8*>((const char*)Ks + KSWZ(32 + r32, cb));
;     p0 = __builtin_amdgcn_mfma_f32_32x32x16_bf16(b0, qr[d0], p0, 0, 0, 0);
;     p1 = __builtin_amdgcn_mfma_f32_32x32x16_bf16(b1, qr[d0], p1, 0, 0, 0); }
; }
; __device__ __forceinline__ int v_st(int k, int c) { const int kk = (k & ~0xC) | ((k & 4) << 1) | ((k & 8) >> 1); return ((kk >> 3) * 4 + (c >> 5)) * 512 + ((kk & 7) * 32 + (c & 31)) * 2; }
; __device__ __forceinline__ int v_rd_base(int lane) { return ((lane & 3) << 3) | (((lane >> 2) & 3) << 6) | (((lane >> 4) & 1) << 5) | (((lane >> 5) & 1) << 8); }
; template <int OFF> __device__ __forceinline__ s16x4 tr_read(int vb) {
;   s16x4 r; asm volatile("ds_read_b64_tr_b16 %0, %1 offset:%2" : "=&v"(r) : "v"(vb), "i"(OFF) : "memory"); return r;
; }
; template <int D0> __device__ __forceinline__ void pv_one(f32x16& od, int vb, bf16x8 pa0, bf16x8 pa1, bf16x8 pa2, bf16x8 pa3) {
;   const s16x4 l0 = tr_read<v_rd_off(D0, 0, 0)>(vb), h0 = tr_read<v_rd_off(D0, 0, 1)>(vb), l1 = tr_read<v_rd_off(D0, 1, 0)>(vb), h1 = tr_read<v_rd_off(D0, 1, 1)>(vb);
; __device__ __forceinline__ void attn_unit_fast(const bf16* __restrict__ Qb, const bf16* __restrict__ Kh, const bf16* __restrict__ Vh, bf16* __restrict__ Ob, int NT, char* lds, int t0, const float* __restrict__ qg) {
;     ...
;   for (int j = 1; j + 1 < NT; j += 2) {
;     SBAR(); qkt(pB0, pB1, (bf16*)((char*)K_lds + SHM_K), qr, r32, hi);
;     finishSM_fast(pA0, pA1, l_reg, pa0, pa1, pa2, pa3); SBAR();
;     if (j + 2 < NT) SLOAD(SO, (j + 2) * KVBLK); SBAR();
;     pv_d0(o, vb0, pa0, pa1, pa2, pa3); partialSM_fast(pB0, pB1);
;     __syncthreads(); SWAIT(); SWRITE(0, SE);
;     __syncthreads();
;     SBAR(); qkt(pA0, pA1, K_lds, qr, r32, hi);
;     if (j + 2 == NT) MASKLAST(pA0, pA1);
;     finishSM_fast(pB0, pB1, l_reg, pa0, pa1, pa2, pa3); SBAR();
;     if (j + 3 < NT) SLOAD(SE, (j + 3) * KVBLK); SBAR();
;     pv_d0(o, vb0 + (int)SHM_V, pa0, pa1, pa2, pa3); partialSM_fast(pA0, pA1);
;     __syncthreads(); SWAIT(); SWRITE(1, SO);
;     __syncthreads();
	v_mfma_f32_32x32x16_bf16 v[48:63], v[140:143], v[234:237], v[48:63]
	ds_read_b64_tr_b16 v[234:235], v188 offset:57856
	ds_read_b64_tr_b16 v[236:237], v188 offset:59904
	v_exp_f32_e32 v66, v66
	v_exp_f32_e32 v67, v67
	v_mfma_f32_32x32x16_bf16 v[0:15], v[144:147], v[240:243], v[0:15]
	ds_read_b64_tr_b16 v[240:241], v188 offset:58368
	ds_read_b64_tr_b16 v[242:243], v188 offset:60416
	v_exp_f32_e32 v68, v68
	v_exp_f32_e32 v69, v69
	v_cvt_pk_bf16_f32 v140, v96, v97
	v_cvt_pk_bf16_f32 v141, v98, v99
	v_mfma_f32_32x32x16_bf16 v[16:31], v[144:147], v[180:183], v[16:31]
	ds_read_b64_tr_b16 v[180:181], v188 offset:58880
	ds_read_b64_tr_b16 v[182:183], v188 offset:60928
	v_exp_f32_e32 v70, v70
	v_exp_f32_e32 v71, v71
	v_cvt_pk_bf16_f32 v142, v100, v101
	v_cvt_pk_bf16_f32 v143, v102, v103
	s_waitcnt lgkmcnt(6)
	v_mfma_f32_32x32x16_bf16 v[32:47], v[144:147], v[222:225], v[32:47]
	ds_read_b64_tr_b16 v[222:223], v188 offset:61440
	ds_read_b64_tr_b16 v[224:225], v188 offset:63488
	v_exp_f32_e32 v72, v72
	v_exp_f32_e32 v73, v73
	v_mfma_f32_32x32x16_bf16 v[48:63], v[144:147], v[226:229], v[48:63]
	ds_read_b64_tr_b16 v[226:227], v188 offset:61952
	ds_read_b64_tr_b16 v[228:229], v188 offset:64000
	v_exp_f32_e32 v74, v74
	v_exp_f32_e32 v75, v75
	v_mfma_f32_32x32x16_bf16 v[0:15], v[152:155], v[230:233], v[0:15]
	ds_read_b64_tr_b16 v[230:231], v188 offset:62464
	ds_read_b64_tr_b16 v[232:233], v188 offset:64512
	v_exp_f32_e32 v76, v76
	v_exp_f32_e32 v77, v77
	v_cvt_pk_bf16_f32 v144, v104, v105
	v_cvt_pk_bf16_f32 v145, v106, v107
	s_waitcnt lgkmcnt(6)
	v_mfma_f32_32x32x16_bf16 v[16:31], v[152:155], v[234:237], v[16:31]
	ds_read_b64_tr_b16 v[234:235], v188 offset:62976
	ds_read_b64_tr_b16 v[236:237], v188 offset:65024
	v_exp_f32_e32 v78, v78
	v_exp_f32_e32 v79, v79
	v_cvt_pk_bf16_f32 v146, v108, v109
	v_cvt_pk_bf16_f32 v147, v110, v111
	s_waitcnt vmcnt(6)
	s_barrier
	v_mfma_f32_32x32x16_bf16 v[32:47], v[152:155], v[240:243], v[32:47]
	s_add_u32 m0, s5, 0x8000
	v_add_f32_e32 v238, v96, v97
	global_load_lds_dwordx4 v253, s[0:1]
	v_add_f32_e32 v238, v98, v238
	v_add_f32_e32 v238, v99, v238
	v_mfma_f32_32x32x16_bf16 v[48:63], v[152:155], v[180:183], v[48:63]
	s_add_u32 m0, s5, 0xa000
	v_add_f32_e32 v238, v100, v238
	global_load_lds_dwordx4 v254, s[0:1]
	v_add_f32_e32 v238, v101, v238
	v_add_f32_e32 v238, v102, v238
	s_add_u32 s0, s0, 0x4000
	s_addc_u32 s1, s1, 0
	s_waitcnt lgkmcnt(2)
	v_mfma_f32_32x32x16_bf16 v[0:15], v[156:159], v[222:225], v[0:15]
	v_add_f32_e32 v238, v103, v238
	v_add_f32_e32 v238, v104, v238
	v_add_f32_e32 v238, v105, v238
	ds_read_b128 v[206:209], v194 offset:16384
	ds_read_b128 v[210:213], v196 offset:16384
	v_mfma_f32_32x32x16_bf16 v[16:31], v[156:159], v[226:229], v[16:31]
	v_add_f32_e32 v238, v106, v238
	v_add_f32_e32 v238, v107, v238
	v_add_f32_e32 v238, v108, v238
	ds_read_b128 v[214:217], v198 offset:16384
	ds_read_b128 v[218:221], v199 offset:16384
	v_mfma_f32_32x32x16_bf16 v[32:47], v[156:159], v[230:233], v[32:47]
	v_add_f32_e32 v238, v109, v238
	v_add_f32_e32 v238, v110, v238
	ds_read_b128 v[160:163], v200 offset:16384
	ds_read_b128 v[164:167], v201 offset:16384
	s_waitcnt lgkmcnt(6)
	v_mfma_f32_32x32x16_bf16 v[48:63], v[156:159], v[234:237], v[48:63]
	v_add_f32_e32 v238, v111, v238
	v_add_f32_e32 v197, v238, v197
	ds_read_b128 v[168:171], v202 offset:16384
	ds_read_b128 v[172:175], v203 offset:16384
	s_sub_u32 s4, s4, 1
	s_cmp_lg_u32 s4, 0
	s_cbranch_scc1 .Lattn_loop
; #define SBAR() __builtin_amdgcn_sched_barrier(0)
; __device__ __forceinline__ int crow(int r, int hi) { return (r & 3) + 8 * (r >> 2) + 4 * hi; }
; template <int D0> __device__ __forceinline__ void pv_one(f32x16& od, int vb, bf16x8 pa0, bf16x8 pa1, bf16x8 pa2, bf16x8 pa3) {
;   const s16x4 l0 = tr_read<v_rd_off(D0, 0, 0)>(vb), h0 = tr_read<v_rd_off(D0, 0, 1)>(vb), l1 = tr_read<v_rd_off(D0, 1, 0)>(vb), h1 = tr_read<v_rd_off(D0, 1, 1)>(vb);
;   const s16x4 l2 = tr_read<v_rd_off(D0, 2, 0)>(vb), h2 = tr_read<v_rd_off(D0, 2, 1)>(vb), l3 = tr_read<v_rd_off(D0, 3, 0)>(vb), h3 = tr_read<v_rd_off(D0, 3, 1)>(vb);
;   asm volatile("s_waitcnt lgkmcnt(0)" ::: "memory"); SBAR();
;     ...
;   od = __builtin_amdgcn_mfma_f32_32x32x16_bf16(pa0, PK(l0, h0), od, 0, 0, 0);
;   od = __builtin_amdgcn_mfma_f32_32x32x16_bf16(pa1, PK(l1, h1), od, 0, 0, 0);
;   od = __builtin_amdgcn_mfma_f32_32x32x16_bf16(pa2, PK(l2, h2), od, 0, 0, 0);
;   od = __builtin_amdgcn_mfma_f32_32x32x16_bf16(pa3, PK(l3, h3), od, 0, 0, 0);
; __device__ __forceinline__ void attn_unit_fast(const bf16* __restrict__ Qb, const bf16* __restrict__ Kh, const bf16* __restrict__ Vh, bf16* __restrict__ Ob, int NT, char* lds, int t0, const float* __restrict__ qg) {
;     ...
;   finishSM_fast(pA0, pA1, l_reg, pa0, pa1, pa2, pa3); SBAR();
;   pv_d0(o, vb0, pa0, pa1, pa2, pa3);
;   { int r32e = r32; asm volatile("" : "+v"(r32e)); if (hi == 0) li_l[r32e] = l_reg; }
;   asm volatile("s_waitcnt lgkmcnt(0)" ::: "memory");
;   float rli[16];
; #pragma unroll
;   for (int r = 0; r < 16; ++r) rli[r] = __builtin_amdgcn_rcpf(li_l[crow(r, hi)]);
	v_cvt_pk_bf16_f32 v152, v64, v65
	v_cvt_pk_bf16_f32 v153, v66, v67
	v_cvt_pk_bf16_f32 v154, v68, v69
	v_cvt_pk_bf16_f32 v155, v70, v71
	v_cvt_pk_bf16_f32 v156, v72, v73
	v_cvt_pk_bf16_f32 v157, v74, v75
	v_cvt_pk_bf16_f32 v158, v76, v77
	v_cvt_pk_bf16_f32 v159, v78, v79
	v_add_f32_e32 v239, v64, v65
	v_add_f32_e32 v239, v66, v239
	v_add_f32_e32 v239, v67, v239
	v_add_f32_e32 v239, v68, v239
	v_add_f32_e32 v239, v69, v239
	v_add_f32_e32 v239, v70, v239
	v_add_f32_e32 v239, v71, v239
	v_add_f32_e32 v239, v72, v239
	v_add_f32_e32 v239, v73, v239
	v_add_f32_e32 v239, v74, v239
	v_add_f32_e32 v239, v75, v239
	v_add_f32_e32 v239, v76, v239
	v_add_f32_e32 v239, v77, v239
	v_add_f32_e32 v239, v78, v239
	v_add_f32_e32 v239, v79, v239
	v_add_f32_e32 v197, v239, v197
	s_waitcnt lgkmcnt(0)
	ds_read_b64_tr_b16 v[222:223], v188
	ds_read_b64_tr_b16 v[224:225], v188 offset:2048
	ds_read_b64_tr_b16 v[226:227], v188 offset:512
	ds_read_b64_tr_b16 v[228:229], v188 offset:2560
	ds_read_b64_tr_b16 v[230:231], v188 offset:1024
	ds_read_b64_tr_b16 v[232:233], v188 offset:3072
	ds_read_b64_tr_b16 v[234:235], v188 offset:1536
	ds_read_b64_tr_b16 v[236:237], v188 offset:3584
	ds_read_b64_tr_b16 v[240:241], v188 offset:4096
	ds_read_b64_tr_b16 v[242:243], v188 offset:6144
	ds_read_b64_tr_b16 v[180:181], v188 offset:4608
	ds_read_b64_tr_b16 v[182:183], v188 offset:6656
	s_waitcnt lgkmcnt(6)
	v_mfma_f32_32x32x16_bf16 v[0:15], v[140:143], v[222:225], v[0:15]
	ds_read_b64_tr_b16 v[222:223], v188 offset:5120
	ds_read_b64_tr_b16 v[224:225], v188 offset:7168
	v_mfma_f32_32x32x16_bf16 v[16:31], v[140:143], v[226:229], v[16:31]
	ds_read_b64_tr_b16 v[226:227], v188 offset:5632
	ds_read_b64_tr_b16 v[228:229], v188 offset:7680
	v_mfma_f32_32x32x16_bf16 v[32:47], v[140:143], v[230:233], v[32:47]
	ds_read_b64_tr_b16 v[230:231], v188 offset:8192
	ds_read_b64_tr_b16 v[232:233], v188 offset:10240
	s_waitcnt lgkmcnt(6)
	v_mfma_f32_32x32x16_bf16 v[48:63], v[140:143], v[234:237], v[48:63]
	ds_read_b64_tr_b16 v[234:235], v188 offset:8704
	ds_read_b64_tr_b16 v[236:237], v188 offset:10752
	v_mfma_f32_32x32x16_bf16 v[0:15], v[144:147], v[240:243], v[0:15]
	ds_read_b64_tr_b16 v[240:241], v188 offset:9216
	ds_read_b64_tr_b16 v[242:243], v188 offset:11264
	v_mfma_f32_32x32x16_bf16 v[16:31], v[144:147], v[180:183], v[16:31]
	ds_read_b64_tr_b16 v[180:181], v188 offset:9728
	ds_read_b64_tr_b16 v[182:183], v188 offset:11776
	s_waitcnt lgkmcnt(6)
	v_mfma_f32_32x32x16_bf16 v[32:47], v[144:147], v[222:225], v[32:47]
	ds_read_b64_tr_b16 v[222:223], v188 offset:12288
	ds_read_b64_tr_b16 v[224:225], v188 offset:14336
	v_mfma_f32_32x32x16_bf16 v[48:63], v[144:147], v[226:229], v[48:63]
	ds_read_b64_tr_b16 v[226:227], v188 offset:12800
	ds_read_b64_tr_b16 v[228:229], v188 offset:14848
	v_mfma_f32_32x32x16_bf16 v[0:15], v[152:155], v[230:233], v[0:15]
	ds_read_b64_tr_b16 v[230:231], v188 offset:13312
	ds_read_b64_tr_b16 v[232:233], v188 offset:15360
	s_waitcnt lgkmcnt(6)
	v_mfma_f32_32x32x16_bf16 v[16:31], v[152:155], v[234:237], v[16:31]
	ds_read_b64_tr_b16 v[234:235], v188 offset:13824
	ds_read_b64_tr_b16 v[236:237], v188 offset:15872
	v_mfma_f32_32x32x16_bf16 v[32:47], v[152:155], v[240:243], v[32:47]
	v_mfma_f32_32x32x16_bf16 v[48:63], v[152:155], v[180:183], v[48:63]
	s_waitcnt lgkmcnt(2)
	v_mfma_f32_32x32x16_bf16 v[0:15], v[156:159], v[222:225], v[0:15]
	v_mfma_f32_32x32x16_bf16 v[16:31], v[156:159], v[226:229], v[16:31]
	v_mfma_f32_32x32x16_bf16 v[32:47], v[156:159], v[230:233], v[32:47]
	s_waitcnt lgkmcnt(0)
	v_mfma_f32_32x32x16_bf16 v[48:63], v[156:159], v[234:237], v[48:63]
	s_waitcnt vmcnt(0)
	s_setprio 0
	v_mov_b32_e32 v64, v197
	v_mov_b32_e32 v65, v197
	v_and_b32_e32 v80, 0x3fffffc0, v195
	s_mov_b32 s0, 0x10000
	v_permlane32_swap_b32_e32 v64, v65
	v_lshl_add_u32 v80, v80, 2, s0
	v_cmp_gt_u32_e32 vcc, 32, v179
	v_add_f32_e32 v64, v64, v65
	v_mov_b32_e32 v66, v191
	v_add_f32_e32 v64, 0xc2400000, v64
	s_nop 3
	s_and_saveexec_b64 s[0:1], vcc
	s_cbranch_execz .LBB0_439
	v_lshl_add_u32 v65, v66, 2, v80
	ds_write_b32 v65, v64
	s_branch .LBB0_439
